# c29 + bf16 epilogue stores of P8 (kh==1) and P10 widened: adjacent 16-column tile pairs exchanged across lane groups (v_permlane32_swap + v_permlane16_swap) and written as one dwordx4; P10 second-half
# speedup vs baseline: 1.0179x; 1.0072x over previous
; __device__ __forceinline__ unsigned cvt_pk_bf16(float lo, float hi) { unsigned r; asm volatile("v_cvt_pk_bf16_f32 %0, %1, %2" : "=v"(r) : "v"(lo), "v"(hi)); return r; }
;     __device__ __forceinline__ void operator()(f32x4 (&acc)[2][2][4][2], const Unit& u, int wr, int wc, int fr, int fq) const {
;     ...
;                         const unsigned long long wb = wbv[m][bj][n];
;                         f32x4 eb;
;                         eb[0] = __expf(-fmaxf(__uint_as_float((unsigned)(wb & 0xffffull) << 16), -60.f)); eb[1] = __expf(-fmaxf(__uint_as_float((unsigned)((wb >> 16) & 0xffffull) << 16), -60.f));
;                         eb[2] = __expf(-fmaxf(__uint_as_float((unsigned)((wb >> 32) & 0xffffull) << 16), -60.f)); eb[3] = __expf(-fmaxf(__uint_as_float((unsigned)((wb >> 48) & 0xffffull) << 16), -60.f));
;                         if (u.kh == 0) {
;                             const unsigned long long wa = wav[m][bj][n];
;                             f32x4 ea;
;                             ea[0] = __expf(-__uint_as_float((unsigned)(wa & 0xffffull) << 16)); ea[1] = __expf(-__uint_as_float((unsigned)((wa >> 16) & 0xffffull) << 16));
;                             ea[2] = __expf(-__uint_as_float((unsigned)((wa >> 32) & 0xffffull) << 16)); ea[3] = __expf(-__uint_as_float((unsigned)((wa >> 48) & 0xffffull) << 16));
; #pragma unroll
;                             for (int e_ = 0; e_ < 4; ++e_) acc[ai][bj][m][n][e_] *= (1.0f + eb[e_]) * __builtin_amdgcn_rcpf(1.0f + ea[e_]);
;                         } else {
;                             f32x4 o;
; #pragma unroll
;                             for (int e_ = 0; e_ < 4; ++e_) o[e_] = acc[ai][bj][m][n][e_] * __builtin_amdgcn_rcpf(1.0f + eb[e_]);
;                             *(unsigned long long*)(merged + off + bj * HALF + 16 * n) = (unsigned long long)cvt_pk_bf16(o[0], o[1]) | ((unsigned long long)cvt_pk_bf16(o[2], o[3]) << 32);
.LBB0_931:
	s_waitcnt vmcnt(0)
	v_lshlrev_b32_e32 v1, 16, v212
	v_max_f32_e32 v1, v1, v1
	v_max_f32_e32 v1, 0xc2700000, v1
	v_mul_f32_e32 v1, 0xbfb8aa3b, v1
	v_exp_f32_e32 v218, v1
	v_and_b32_e32 v1, 0xffff0000, v212
	v_max_f32_e32 v1, v1, v1
	v_max_f32_e32 v1, 0xc2700000, v1
	v_mul_f32_e32 v1, 0xbfb8aa3b, v1
	v_exp_f32_e32 v219, v1
	v_alignbit_b32 v1, v213, v212, 16
	v_and_b32_e32 v1, 0xffff0000, v1
	v_max_f32_e32 v1, v1, v1
	v_max_f32_e32 v1, 0xc2700000, v1
	v_mul_f32_e32 v1, 0xbfb8aa3b, v1
	v_exp_f32_e32 v220, v1
	v_and_b32_e32 v1, 0xffff0000, v213
	v_max_f32_e32 v1, v1, v1
	v_max_f32_e32 v1, 0xc2700000, v1
	v_mul_f32_e32 v1, 0xbfb8aa3b, v1
	v_exp_f32_e32 v221, v1
	v_or_b32_e32 v2, s21, v225
	v_lshlrev_b64 v[228:229], 11, v[144:145]
	v_ashrrev_i32_e32 v3, 31, v2
	v_cndmask_b32_e64 v1, 0, 1, s[38:39]
	v_lshl_add_u64 v[212:213], s[14:15], 0, v[228:229]
	s_mov_b64 s[42:43], -1
	v_cmp_ne_u32_e64 s[4:5], 1, v1
	s_andn2_b64 vcc, exec, s[38:39]
	v_lshl_add_u64 v[212:213], v[2:3], 1, v[212:213]
	s_cbranch_vccnz .LBB0_933
	v_add_f32_e32 v1, 1.0, v218
	v_add_f32_e32 v145, 1.0, v219
	v_add_f32_e32 v222, 1.0, v220
	v_add_f32_e32 v227, 1.0, v221
	v_rcp_f32_e32 v1, v1
	v_rcp_f32_e32 v145, v145
	v_rcp_f32_e32 v222, v222
	v_rcp_f32_e32 v227, v227
	s_mov_b64 s[42:43], 0
	v_mul_f32_e32 v1, v128, v1
	v_mul_f32_e32 v145, v129, v145
	v_mul_f32_e32 v222, v130, v222
	v_mul_f32_e32 v227, v131, v227
	v_cvt_pk_bf16_f32 v228, v1, v145
	v_cvt_pk_bf16_f32 v229, v222, v227
	v_and_b32_e32 v244, 48, v254
	v_mov_b32_e32 v245, 0
	v_lshrrev_b32_e32 v244, 1, v244
	v_mov_b32_e32 v240, v228
	v_mov_b32_e32 v241, v229

; __device__ __forceinline__ unsigned cvt_pk_bf16(float lo, float hi) { unsigned r; asm volatile("v_cvt_pk_bf16_f32 %0, %1, %2" : "=v"(r) : "v"(lo), "v"(hi)); return r; }
;     __device__ __forceinline__ void operator()(f32x4 (&acc)[2][2][4][2], const Unit& u, int wr, int wc, int fr, int fq) const {
;     ...
;                         const unsigned long long wb = wbv[m][bj][n];
;                         f32x4 eb;
;                         eb[0] = __expf(-fmaxf(__uint_as_float((unsigned)(wb & 0xffffull) << 16), -60.f)); eb[1] = __expf(-fmaxf(__uint_as_float((unsigned)((wb >> 16) & 0xffffull) << 16), -60.f));
;                         eb[2] = __expf(-fmaxf(__uint_as_float((unsigned)((wb >> 32) & 0xffffull) << 16), -60.f)); eb[3] = __expf(-fmaxf(__uint_as_float((unsigned)((wb >> 48) & 0xffffull) << 16), -60.f));
;                         if (u.kh == 0) {
;                             const unsigned long long wa = wav[m][bj][n];
;                             f32x4 ea;
;                             ea[0] = __expf(-__uint_as_float((unsigned)(wa & 0xffffull) << 16)); ea[1] = __expf(-__uint_as_float((unsigned)((wa >> 16) & 0xffffull) << 16));
;                             ea[2] = __expf(-__uint_as_float((unsigned)((wa >> 32) & 0xffffull) << 16)); ea[3] = __expf(-__uint_as_float((unsigned)((wa >> 48) & 0xffffull) << 16));
; #pragma unroll
;                             for (int e_ = 0; e_ < 4; ++e_) acc[ai][bj][m][n][e_] *= (1.0f + eb[e_]) * __builtin_amdgcn_rcpf(1.0f + ea[e_]);
;                         } else {
;                             f32x4 o;
; #pragma unroll
;                             for (int e_ = 0; e_ < 4; ++e_) o[e_] = acc[ai][bj][m][n][e_] * __builtin_amdgcn_rcpf(1.0f + eb[e_]);
;                             *(unsigned long long*)(merged + off + bj * HALF + 16 * n) = (unsigned long long)cvt_pk_bf16(o[0], o[1]) | ((unsigned long long)cvt_pk_bf16(o[2], o[3]) << 32);
.LBB0_935:
	v_lshlrev_b32_e32 v1, 16, v214
	v_max_f32_e32 v1, v1, v1
	v_max_f32_e32 v1, 0xc2700000, v1
	v_mul_f32_e32 v1, 0xbfb8aa3b, v1
	v_exp_f32_e32 v216, v1
	v_and_b32_e32 v1, 0xffff0000, v214
	v_max_f32_e32 v1, v1, v1
	v_max_f32_e32 v1, 0xc2700000, v1
	v_mul_f32_e32 v1, 0xbfb8aa3b, v1
	v_exp_f32_e32 v217, v1
	v_alignbit_b32 v1, v215, v214, 16
	v_and_b32_e32 v1, 0xffff0000, v1
	v_max_f32_e32 v1, v1, v1
	v_max_f32_e32 v1, 0xc2700000, v1
	v_mul_f32_e32 v1, 0xbfb8aa3b, v1
	v_exp_f32_e32 v214, v1
	v_and_b32_e32 v1, 0xffff0000, v215
	v_max_f32_e32 v1, v1, v1
	v_max_f32_e32 v1, 0xc2700000, v1
	v_mul_f32_e32 v1, 0xbfb8aa3b, v1
	v_exp_f32_e32 v215, v1
	s_and_b64 vcc, exec, s[4:5]
	s_mov_b64 s[38:39], -1
	s_cbranch_vccnz .LBB0_937
	v_add_f32_e32 v219, 1.0, v215
	v_add_f32_e32 v1, 1.0, v216
	v_add_f32_e32 v145, 1.0, v217
	v_add_f32_e32 v218, 1.0, v214
	v_rcp_f32_e32 v219, v219
	v_rcp_f32_e32 v1, v1
	v_rcp_f32_e32 v145, v145
	v_rcp_f32_e32 v218, v218
	v_mul_f32_e32 v219, v127, v219
	s_mov_b64 s[38:39], 0
	v_mul_f32_e32 v1, v124, v1
	v_mul_f32_e32 v145, v125, v145
	v_mul_f32_e32 v220, v126, v218
	v_cvt_pk_bf16_f32 v218, v1, v145
	v_cvt_pk_bf16_f32 v219, v220, v219
	v_mov_b32_e32 v242, v218
	v_mov_b32_e32 v243, v219
	v_lshl_add_u64 v[246:247], v[212:213], 0, v[244:245]
	s_nop 0
	v_permlane32_swap_b32_e32 v240, v242
	v_permlane32_swap_b32_e32 v241, v243
	s_nop 0
	v_permlane16_swap_b32_e32 v240, v242
	v_permlane16_swap_b32_e32 v241, v243
	s_nop 1
	global_store_dwordx4 v[246:247], v[240:243], off

; __device__ __forceinline__ unsigned cvt_pk_bf16(float lo, float hi) { unsigned r; asm volatile("v_cvt_pk_bf16_f32 %0, %1, %2" : "=v"(r) : "v"(lo), "v"(hi)); return r; }
;     __device__ __forceinline__ void operator()(f32x4 (&acc)[2][2][4][2], const Unit& u, int wr, int wc, int fr, int fq) const {
;     ...
;                         const unsigned long long wb = wbv[m][bj][n];
;                         f32x4 eb;
;                         eb[0] = __expf(-fmaxf(__uint_as_float((unsigned)(wb & 0xffffull) << 16), -60.f)); eb[1] = __expf(-fmaxf(__uint_as_float((unsigned)((wb >> 16) & 0xffffull) << 16), -60.f));
;                         eb[2] = __expf(-fmaxf(__uint_as_float((unsigned)((wb >> 32) & 0xffffull) << 16), -60.f)); eb[3] = __expf(-fmaxf(__uint_as_float((unsigned)((wb >> 48) & 0xffffull) << 16), -60.f));
;                         if (u.kh == 0) {
;                             const unsigned long long wa = wav[m][bj][n];
;                             f32x4 ea;
;                             ea[0] = __expf(-__uint_as_float((unsigned)(wa & 0xffffull) << 16)); ea[1] = __expf(-__uint_as_float((unsigned)((wa >> 16) & 0xffffull) << 16));
;                             ea[2] = __expf(-__uint_as_float((unsigned)((wa >> 32) & 0xffffull) << 16)); ea[3] = __expf(-__uint_as_float((unsigned)((wa >> 48) & 0xffffull) << 16));
; #pragma unroll
;                             for (int e_ = 0; e_ < 4; ++e_) acc[ai][bj][m][n][e_] *= (1.0f + eb[e_]) * __builtin_amdgcn_rcpf(1.0f + ea[e_]);
;                         } else {
;                             f32x4 o;
; #pragma unroll
;                             for (int e_ = 0; e_ < 4; ++e_) o[e_] = acc[ai][bj][m][n][e_] * __builtin_amdgcn_rcpf(1.0f + eb[e_]);
;                             *(unsigned long long*)(merged + off + bj * HALF + 16 * n) = (unsigned long long)cvt_pk_bf16(o[0], o[1]) | ((unsigned long long)cvt_pk_bf16(o[2], o[3]) << 32);
.LBB0_939:
	v_lshlrev_b32_e32 v1, 16, v208
	v_max_f32_e32 v1, v1, v1
	v_max_f32_e32 v1, 0xc2700000, v1
	v_mul_f32_e32 v1, 0xbfb8aa3b, v1
	v_exp_f32_e32 v210, v1
	v_and_b32_e32 v1, 0xffff0000, v208
	v_max_f32_e32 v1, v1, v1
	v_max_f32_e32 v1, 0xc2700000, v1
	v_mul_f32_e32 v1, 0xbfb8aa3b, v1
	v_exp_f32_e32 v211, v1
	v_alignbit_b32 v1, v209, v208, 16
	v_and_b32_e32 v1, 0xffff0000, v1
	v_max_f32_e32 v1, v1, v1
	v_max_f32_e32 v1, 0xc2700000, v1
	v_mul_f32_e32 v1, 0xbfb8aa3b, v1
	v_exp_f32_e32 v208, v1
	v_and_b32_e32 v1, 0xffff0000, v209
	v_max_f32_e32 v1, v1, v1
	v_max_f32_e32 v1, 0xc2700000, v1
	v_mul_f32_e32 v1, 0xbfb8aa3b, v1
	v_exp_f32_e32 v209, v1
	s_and_b64 vcc, exec, s[4:5]
	s_mov_b64 s[38:39], -1
	s_cbranch_vccnz .LBB0_941
	v_add_f32_e32 v215, 1.0, v209
	v_add_f32_e32 v1, 1.0, v210
	v_add_f32_e32 v145, 1.0, v211
	v_add_f32_e32 v214, 1.0, v208
	v_rcp_f32_e32 v215, v215
	v_rcp_f32_e32 v1, v1
	v_rcp_f32_e32 v145, v145
	v_rcp_f32_e32 v214, v214
	v_mul_f32_e32 v215, v99, v215
	s_mov_b64 s[38:39], 0
	v_mul_f32_e32 v1, v96, v1
	v_mul_f32_e32 v145, v97, v145
	v_mul_f32_e32 v216, v98, v214
	v_cvt_pk_bf16_f32 v214, v1, v145
	v_cvt_pk_bf16_f32 v215, v216, v215
	v_mov_b32_e32 v240, v214
	v_mov_b32_e32 v241, v215

; __device__ __forceinline__ unsigned cvt_pk_bf16(float lo, float hi) { unsigned r; asm volatile("v_cvt_pk_bf16_f32 %0, %1, %2" : "=v"(r) : "v"(lo), "v"(hi)); return r; }
;     __device__ __forceinline__ void operator()(f32x4 (&acc)[2][2][4][2], const Unit& u, int wr, int wc, int fr, int fq) const {
;     ...
;                         const unsigned long long wb = wbv[m][bj][n];
;                         f32x4 eb;
;                         eb[0] = __expf(-fmaxf(__uint_as_float((unsigned)(wb & 0xffffull) << 16), -60.f)); eb[1] = __expf(-fmaxf(__uint_as_float((unsigned)((wb >> 16) & 0xffffull) << 16), -60.f));
;                         eb[2] = __expf(-fmaxf(__uint_as_float((unsigned)((wb >> 32) & 0xffffull) << 16), -60.f)); eb[3] = __expf(-fmaxf(__uint_as_float((unsigned)((wb >> 48) & 0xffffull) << 16), -60.f));
;                         if (u.kh == 0) {
;                             const unsigned long long wa = wav[m][bj][n];
;                             f32x4 ea;
;                             ea[0] = __expf(-__uint_as_float((unsigned)(wa & 0xffffull) << 16)); ea[1] = __expf(-__uint_as_float((unsigned)((wa >> 16) & 0xffffull) << 16));
;                             ea[2] = __expf(-__uint_as_float((unsigned)((wa >> 32) & 0xffffull) << 16)); ea[3] = __expf(-__uint_as_float((unsigned)((wa >> 48) & 0xffffull) << 16));
; #pragma unroll
;                             for (int e_ = 0; e_ < 4; ++e_) acc[ai][bj][m][n][e_] *= (1.0f + eb[e_]) * __builtin_amdgcn_rcpf(1.0f + ea[e_]);
;                         } else {
;                             f32x4 o;
; #pragma unroll
;                             for (int e_ = 0; e_ < 4; ++e_) o[e_] = acc[ai][bj][m][n][e_] * __builtin_amdgcn_rcpf(1.0f + eb[e_]);
;                             *(unsigned long long*)(merged + off + bj * HALF + 16 * n) = (unsigned long long)cvt_pk_bf16(o[0], o[1]) | ((unsigned long long)cvt_pk_bf16(o[2], o[3]) << 32);
.LBB0_943:
	v_lshlrev_b32_e32 v1, 16, v204
	v_max_f32_e32 v1, v1, v1
	v_max_f32_e32 v1, 0xc2700000, v1
	v_mul_f32_e32 v1, 0xbfb8aa3b, v1
	v_exp_f32_e32 v206, v1
	v_and_b32_e32 v1, 0xffff0000, v204
	v_max_f32_e32 v1, v1, v1
	v_max_f32_e32 v1, 0xc2700000, v1
	v_mul_f32_e32 v1, 0xbfb8aa3b, v1
	v_exp_f32_e32 v207, v1
	v_alignbit_b32 v1, v205, v204, 16
	v_and_b32_e32 v1, 0xffff0000, v1
	v_max_f32_e32 v1, v1, v1
	v_max_f32_e32 v1, 0xc2700000, v1
	v_mul_f32_e32 v1, 0xbfb8aa3b, v1
	v_exp_f32_e32 v204, v1
	v_and_b32_e32 v1, 0xffff0000, v205
	v_max_f32_e32 v1, v1, v1
	v_max_f32_e32 v1, 0xc2700000, v1
	v_mul_f32_e32 v1, 0xbfb8aa3b, v1
	v_exp_f32_e32 v205, v1
	s_and_b64 vcc, exec, s[4:5]
	s_mov_b64 s[38:39], -1
	s_cbranch_vccnz .LBB0_945
	v_add_f32_e32 v209, 1.0, v205
	v_add_f32_e32 v1, 1.0, v206
	v_add_f32_e32 v145, 1.0, v207
	v_add_f32_e32 v208, 1.0, v204
	v_rcp_f32_e32 v209, v209
	v_rcp_f32_e32 v1, v1
	v_rcp_f32_e32 v145, v145
	v_rcp_f32_e32 v208, v208
	v_mul_f32_e32 v209, v95, v209
	s_mov_b64 s[38:39], 0
	v_mul_f32_e32 v1, v92, v1
	v_mul_f32_e32 v145, v93, v145
	v_mul_f32_e32 v210, v94, v208
	v_cvt_pk_bf16_f32 v208, v1, v145
	v_cvt_pk_bf16_f32 v209, v210, v209
	v_mov_b32_e32 v242, v208
	v_mov_b32_e32 v243, v209
	v_lshl_add_u64 v[246:247], v[212:213], 0, v[244:245]
	s_nop 0
	v_permlane32_swap_b32_e32 v240, v242
	v_permlane32_swap_b32_e32 v241, v243
	s_nop 0
	v_permlane16_swap_b32_e32 v240, v242
	v_permlane16_swap_b32_e32 v241, v243
	s_nop 1
	global_store_dwordx4 v[246:247], v[240:243], off offset:256

; __device__ __forceinline__ unsigned cvt_pk_bf16(float lo, float hi) { unsigned r; asm volatile("v_cvt_pk_bf16_f32 %0, %1, %2" : "=v"(r) : "v"(lo), "v"(hi)); return r; }
;     __device__ __forceinline__ void operator()(f32x4 (&acc)[2][2][4][2], const Unit& u, int wr, int wc, int fr, int fq) const {
;     ...
;                         const unsigned long long wb = wbv[m][bj][n];
;                         f32x4 eb;
;                         eb[0] = __expf(-fmaxf(__uint_as_float((unsigned)(wb & 0xffffull) << 16), -60.f)); eb[1] = __expf(-fmaxf(__uint_as_float((unsigned)((wb >> 16) & 0xffffull) << 16), -60.f));
;                         eb[2] = __expf(-fmaxf(__uint_as_float((unsigned)((wb >> 32) & 0xffffull) << 16), -60.f)); eb[3] = __expf(-fmaxf(__uint_as_float((unsigned)((wb >> 48) & 0xffffull) << 16), -60.f));
;                         if (u.kh == 0) {
;                             const unsigned long long wa = wav[m][bj][n];
;                             f32x4 ea;
;                             ea[0] = __expf(-__uint_as_float((unsigned)(wa & 0xffffull) << 16)); ea[1] = __expf(-__uint_as_float((unsigned)((wa >> 16) & 0xffffull) << 16));
;                             ea[2] = __expf(-__uint_as_float((unsigned)((wa >> 32) & 0xffffull) << 16)); ea[3] = __expf(-__uint_as_float((unsigned)((wa >> 48) & 0xffffull) << 16));
; #pragma unroll
;                             for (int e_ = 0; e_ < 4; ++e_) acc[ai][bj][m][n][e_] *= (1.0f + eb[e_]) * __builtin_amdgcn_rcpf(1.0f + ea[e_]);
;                         } else {
;                             f32x4 o;
; #pragma unroll
;                             for (int e_ = 0; e_ < 4; ++e_) o[e_] = acc[ai][bj][m][n][e_] * __builtin_amdgcn_rcpf(1.0f + eb[e_]);
;                             *(unsigned long long*)(merged + off + bj * HALF + 16 * n) = (unsigned long long)cvt_pk_bf16(o[0], o[1]) | ((unsigned long long)cvt_pk_bf16(o[2], o[3]) << 32);
.LBB0_947:
	v_lshlrev_b32_e32 v1, 16, v198
	v_max_f32_e32 v1, v1, v1
	v_max_f32_e32 v1, 0xc2700000, v1
	v_mul_f32_e32 v1, 0xbfb8aa3b, v1
	v_lshlrev_b64 v[204:205], 11, v[200:201]
	v_exp_f32_e32 v200, v1
	v_and_b32_e32 v1, 0xffff0000, v198
	v_max_f32_e32 v1, v1, v1
	v_max_f32_e32 v1, 0xc2700000, v1
	v_mul_f32_e32 v1, 0xbfb8aa3b, v1
	v_exp_f32_e32 v201, v1
	v_alignbit_b32 v1, v199, v198, 16
	v_and_b32_e32 v1, 0xffff0000, v1
	v_max_f32_e32 v1, v1, v1
	v_max_f32_e32 v1, 0xc2700000, v1
	v_mul_f32_e32 v1, 0xbfb8aa3b, v1
	v_exp_f32_e32 v202, v1
	v_and_b32_e32 v1, 0xffff0000, v199
	v_max_f32_e32 v1, v1, v1
	v_max_f32_e32 v1, 0xc2700000, v1
	v_mul_f32_e32 v1, 0xbfb8aa3b, v1
	v_exp_f32_e32 v203, v1
	v_lshl_add_u64 v[198:199], s[14:15], 0, v[204:205]
	s_mov_b64 s[38:39], -1
	s_and_b64 vcc, exec, s[4:5]
	v_lshl_add_u64 v[198:199], v[2:3], 1, v[198:199]
	s_cbranch_vccnz .LBB0_949
	v_add_f32_e32 v205, 1.0, v203
	v_add_f32_e32 v1, 1.0, v200
	v_add_f32_e32 v145, 1.0, v201
	v_add_f32_e32 v204, 1.0, v202
	v_rcp_f32_e32 v205, v205
	v_rcp_f32_e32 v1, v1
	v_rcp_f32_e32 v145, v145
	v_rcp_f32_e32 v204, v204
	v_mul_f32_e32 v205, v123, v205
	s_mov_b64 s[38:39], 0
	v_mul_f32_e32 v1, v120, v1
	v_mul_f32_e32 v145, v121, v145
	v_mul_f32_e32 v206, v122, v204
	v_cvt_pk_bf16_f32 v204, v1, v145
	v_cvt_pk_bf16_f32 v205, v206, v205
	v_and_b32_e32 v244, 48, v254
	v_mov_b32_e32 v245, 0
	v_lshrrev_b32_e32 v244, 1, v244
	v_mov_b32_e32 v240, v204
	v_mov_b32_e32 v241, v205

; __device__ __forceinline__ unsigned cvt_pk_bf16(float lo, float hi) { unsigned r; asm volatile("v_cvt_pk_bf16_f32 %0, %1, %2" : "=v"(r) : "v"(lo), "v"(hi)); return r; }
;     __device__ __forceinline__ void operator()(f32x4 (&acc)[2][2][4][2], const Unit& u, int wr, int wc, int fr, int fq) const {
;     ...
;                         const unsigned long long wb = wbv[m][bj][n];
;                         f32x4 eb;
;                         eb[0] = __expf(-fmaxf(__uint_as_float((unsigned)(wb & 0xffffull) << 16), -60.f)); eb[1] = __expf(-fmaxf(__uint_as_float((unsigned)((wb >> 16) & 0xffffull) << 16), -60.f));
;                         eb[2] = __expf(-fmaxf(__uint_as_float((unsigned)((wb >> 32) & 0xffffull) << 16), -60.f)); eb[3] = __expf(-fmaxf(__uint_as_float((unsigned)((wb >> 48) & 0xffffull) << 16), -60.f));
;                         if (u.kh == 0) {
;                             const unsigned long long wa = wav[m][bj][n];
;                             f32x4 ea;
;                             ea[0] = __expf(-__uint_as_float((unsigned)(wa & 0xffffull) << 16)); ea[1] = __expf(-__uint_as_float((unsigned)((wa >> 16) & 0xffffull) << 16));
;                             ea[2] = __expf(-__uint_as_float((unsigned)((wa >> 32) & 0xffffull) << 16)); ea[3] = __expf(-__uint_as_float((unsigned)((wa >> 48) & 0xffffull) << 16));
; #pragma unroll
;                             for (int e_ = 0; e_ < 4; ++e_) acc[ai][bj][m][n][e_] *= (1.0f + eb[e_]) * __builtin_amdgcn_rcpf(1.0f + ea[e_]);
;                         } else {
;                             f32x4 o;
; #pragma unroll
;                             for (int e_ = 0; e_ < 4; ++e_) o[e_] = acc[ai][bj][m][n][e_] * __builtin_amdgcn_rcpf(1.0f + eb[e_]);
;                             *(unsigned long long*)(merged + off + bj * HALF + 16 * n) = (unsigned long long)cvt_pk_bf16(o[0], o[1]) | ((unsigned long long)cvt_pk_bf16(o[2], o[3]) << 32);
.LBB0_951:
	v_lshlrev_b32_e32 v1, 16, v194
	v_max_f32_e32 v1, v1, v1
	v_max_f32_e32 v1, 0xc2700000, v1
	v_mul_f32_e32 v1, 0xbfb8aa3b, v1
	v_exp_f32_e32 v196, v1
	v_and_b32_e32 v1, 0xffff0000, v194
	v_max_f32_e32 v1, v1, v1
	v_max_f32_e32 v1, 0xc2700000, v1
	v_mul_f32_e32 v1, 0xbfb8aa3b, v1
	v_exp_f32_e32 v197, v1
	v_alignbit_b32 v1, v195, v194, 16
	v_and_b32_e32 v1, 0xffff0000, v1
	v_max_f32_e32 v1, v1, v1
	v_max_f32_e32 v1, 0xc2700000, v1
	v_mul_f32_e32 v1, 0xbfb8aa3b, v1
	v_exp_f32_e32 v194, v1
	v_and_b32_e32 v1, 0xffff0000, v195
	v_max_f32_e32 v1, v1, v1
	v_max_f32_e32 v1, 0xc2700000, v1
	v_mul_f32_e32 v1, 0xbfb8aa3b, v1
	v_exp_f32_e32 v195, v1
	s_and_b64 vcc, exec, s[4:5]
	s_mov_b64 s[38:39], -1
	s_cbranch_vccnz .LBB0_953
	v_add_f32_e32 v201, 1.0, v195
	v_add_f32_e32 v1, 1.0, v196
	v_add_f32_e32 v145, 1.0, v197
	v_add_f32_e32 v200, 1.0, v194
	v_rcp_f32_e32 v201, v201
	v_rcp_f32_e32 v1, v1
	v_rcp_f32_e32 v145, v145
	v_rcp_f32_e32 v200, v200
	v_mul_f32_e32 v201, v119, v201
	s_mov_b64 s[38:39], 0
	v_mul_f32_e32 v1, v116, v1
	v_mul_f32_e32 v145, v117, v145
	v_mul_f32_e32 v202, v118, v200
	v_cvt_pk_bf16_f32 v200, v1, v145
	v_cvt_pk_bf16_f32 v201, v202, v201
	v_mov_b32_e32 v242, v200
	v_mov_b32_e32 v243, v201
	v_lshl_add_u64 v[246:247], v[198:199], 0, v[244:245]
	s_nop 0
	v_permlane32_swap_b32_e32 v240, v242
	v_permlane32_swap_b32_e32 v241, v243
	s_nop 0
	v_permlane16_swap_b32_e32 v240, v242
	v_permlane16_swap_b32_e32 v241, v243
	s_nop 1
	global_store_dwordx4 v[246:247], v[240:243], off

; __device__ __forceinline__ unsigned cvt_pk_bf16(float lo, float hi) { unsigned r; asm volatile("v_cvt_pk_bf16_f32 %0, %1, %2" : "=v"(r) : "v"(lo), "v"(hi)); return r; }
;     __device__ __forceinline__ void operator()(f32x4 (&acc)[2][2][4][2], const Unit& u, int wr, int wc, int fr, int fq) const {
;     ...
;                         const unsigned long long wb = wbv[m][bj][n];
;                         f32x4 eb;
;                         eb[0] = __expf(-fmaxf(__uint_as_float((unsigned)(wb & 0xffffull) << 16), -60.f)); eb[1] = __expf(-fmaxf(__uint_as_float((unsigned)((wb >> 16) & 0xffffull) << 16), -60.f));
;                         eb[2] = __expf(-fmaxf(__uint_as_float((unsigned)((wb >> 32) & 0xffffull) << 16), -60.f)); eb[3] = __expf(-fmaxf(__uint_as_float((unsigned)((wb >> 48) & 0xffffull) << 16), -60.f));
;                         if (u.kh == 0) {
;                             const unsigned long long wa = wav[m][bj][n];
;                             f32x4 ea;
;                             ea[0] = __expf(-__uint_as_float((unsigned)(wa & 0xffffull) << 16)); ea[1] = __expf(-__uint_as_float((unsigned)((wa >> 16) & 0xffffull) << 16));
;                             ea[2] = __expf(-__uint_as_float((unsigned)((wa >> 32) & 0xffffull) << 16)); ea[3] = __expf(-__uint_as_float((unsigned)((wa >> 48) & 0xffffull) << 16));
; #pragma unroll
;                             for (int e_ = 0; e_ < 4; ++e_) acc[ai][bj][m][n][e_] *= (1.0f + eb[e_]) * __builtin_amdgcn_rcpf(1.0f + ea[e_]);
;                         } else {
;                             f32x4 o;
; #pragma unroll
;                             for (int e_ = 0; e_ < 4; ++e_) o[e_] = acc[ai][bj][m][n][e_] * __builtin_amdgcn_rcpf(1.0f + eb[e_]);
;                             *(unsigned long long*)(merged + off + bj * HALF + 16 * n) = (unsigned long long)cvt_pk_bf16(o[0], o[1]) | ((unsigned long long)cvt_pk_bf16(o[2], o[3]) << 32);
.LBB0_955:
	v_lshlrev_b32_e32 v1, 16, v190
	v_max_f32_e32 v1, v1, v1
	v_max_f32_e32 v1, 0xc2700000, v1
	v_mul_f32_e32 v1, 0xbfb8aa3b, v1
	v_exp_f32_e32 v192, v1
	v_and_b32_e32 v1, 0xffff0000, v190
	v_max_f32_e32 v1, v1, v1
	v_max_f32_e32 v1, 0xc2700000, v1
	v_mul_f32_e32 v1, 0xbfb8aa3b, v1
	v_exp_f32_e32 v193, v1
	v_alignbit_b32 v1, v191, v190, 16
	v_and_b32_e32 v1, 0xffff0000, v1
	v_max_f32_e32 v1, v1, v1
	v_max_f32_e32 v1, 0xc2700000, v1
	v_mul_f32_e32 v1, 0xbfb8aa3b, v1
	v_exp_f32_e32 v190, v1
	v_and_b32_e32 v1, 0xffff0000, v191
	v_max_f32_e32 v1, v1, v1
	v_max_f32_e32 v1, 0xc2700000, v1
	v_mul_f32_e32 v1, 0xbfb8aa3b, v1
	v_exp_f32_e32 v191, v1
	s_and_b64 vcc, exec, s[4:5]
	s_mov_b64 s[38:39], -1
	s_cbranch_vccnz .LBB0_957
	v_add_f32_e32 v195, 1.0, v191
	v_add_f32_e32 v1, 1.0, v192
	v_add_f32_e32 v145, 1.0, v193
	v_add_f32_e32 v194, 1.0, v190
	v_rcp_f32_e32 v195, v195
	v_rcp_f32_e32 v1, v1
	v_rcp_f32_e32 v145, v145
	v_rcp_f32_e32 v194, v194
	v_mul_f32_e32 v195, v91, v195
	s_mov_b64 s[38:39], 0
	v_mul_f32_e32 v1, v88, v1
	v_mul_f32_e32 v145, v89, v145
	v_mul_f32_e32 v196, v90, v194
	v_cvt_pk_bf16_f32 v194, v1, v145
	v_cvt_pk_bf16_f32 v195, v196, v195
	v_mov_b32_e32 v240, v194
	v_mov_b32_e32 v241, v195

; __device__ __forceinline__ unsigned cvt_pk_bf16(float lo, float hi) { unsigned r; asm volatile("v_cvt_pk_bf16_f32 %0, %1, %2" : "=v"(r) : "v"(lo), "v"(hi)); return r; }
;     __device__ __forceinline__ void operator()(f32x4 (&acc)[2][2][4][2], const Unit& u, int wr, int wc, int fr, int fq) const {
;     ...
;                         const unsigned long long wb = wbv[m][bj][n];
;                         f32x4 eb;
;                         eb[0] = __expf(-fmaxf(__uint_as_float((unsigned)(wb & 0xffffull) << 16), -60.f)); eb[1] = __expf(-fmaxf(__uint_as_float((unsigned)((wb >> 16) & 0xffffull) << 16), -60.f));
;                         eb[2] = __expf(-fmaxf(__uint_as_float((unsigned)((wb >> 32) & 0xffffull) << 16), -60.f)); eb[3] = __expf(-fmaxf(__uint_as_float((unsigned)((wb >> 48) & 0xffffull) << 16), -60.f));
;                         if (u.kh == 0) {
;                             const unsigned long long wa = wav[m][bj][n];
;                             f32x4 ea;
;                             ea[0] = __expf(-__uint_as_float((unsigned)(wa & 0xffffull) << 16)); ea[1] = __expf(-__uint_as_float((unsigned)((wa >> 16) & 0xffffull) << 16));
;                             ea[2] = __expf(-__uint_as_float((unsigned)((wa >> 32) & 0xffffull) << 16)); ea[3] = __expf(-__uint_as_float((unsigned)((wa >> 48) & 0xffffull) << 16));
; #pragma unroll
;                             for (int e_ = 0; e_ < 4; ++e_) acc[ai][bj][m][n][e_] *= (1.0f + eb[e_]) * __builtin_amdgcn_rcpf(1.0f + ea[e_]);
;                         } else {
;                             f32x4 o;
; #pragma unroll
;                             for (int e_ = 0; e_ < 4; ++e_) o[e_] = acc[ai][bj][m][n][e_] * __builtin_amdgcn_rcpf(1.0f + eb[e_]);
;                             *(unsigned long long*)(merged + off + bj * HALF + 16 * n) = (unsigned long long)cvt_pk_bf16(o[0], o[1]) | ((unsigned long long)cvt_pk_bf16(o[2], o[3]) << 32);
.LBB0_959:
	v_lshlrev_b32_e32 v1, 16, v186
	v_max_f32_e32 v1, v1, v1
	v_max_f32_e32 v1, 0xc2700000, v1
	v_mul_f32_e32 v1, 0xbfb8aa3b, v1
	v_exp_f32_e32 v188, v1
	v_and_b32_e32 v1, 0xffff0000, v186
	v_max_f32_e32 v1, v1, v1
	v_max_f32_e32 v1, 0xc2700000, v1
	v_mul_f32_e32 v1, 0xbfb8aa3b, v1
	v_exp_f32_e32 v189, v1
	v_alignbit_b32 v1, v187, v186, 16
	v_and_b32_e32 v1, 0xffff0000, v1
	v_max_f32_e32 v1, v1, v1
	v_max_f32_e32 v1, 0xc2700000, v1
	v_mul_f32_e32 v1, 0xbfb8aa3b, v1
	v_exp_f32_e32 v186, v1
	v_and_b32_e32 v1, 0xffff0000, v187
	v_max_f32_e32 v1, v1, v1
	v_max_f32_e32 v1, 0xc2700000, v1
	v_mul_f32_e32 v1, 0xbfb8aa3b, v1
	v_exp_f32_e32 v187, v1
	s_and_b64 vcc, exec, s[4:5]
	s_mov_b64 s[38:39], -1
	s_cbranch_vccnz .LBB0_961
	v_add_f32_e32 v191, 1.0, v187
	v_add_f32_e32 v1, 1.0, v188
	v_add_f32_e32 v145, 1.0, v189
	v_add_f32_e32 v190, 1.0, v186
	v_rcp_f32_e32 v191, v191
	v_rcp_f32_e32 v1, v1
	v_rcp_f32_e32 v145, v145
	v_rcp_f32_e32 v190, v190
	v_mul_f32_e32 v191, v87, v191
	s_mov_b64 s[38:39], 0
	v_mul_f32_e32 v1, v84, v1
	v_mul_f32_e32 v145, v85, v145
	v_mul_f32_e32 v192, v86, v190
	v_cvt_pk_bf16_f32 v190, v1, v145
	v_cvt_pk_bf16_f32 v191, v192, v191
	v_mov_b32_e32 v242, v190
	v_mov_b32_e32 v243, v191
	v_lshl_add_u64 v[246:247], v[198:199], 0, v[244:245]
	s_nop 0
	v_permlane32_swap_b32_e32 v240, v242
	v_permlane32_swap_b32_e32 v241, v243
	s_nop 0
	v_permlane16_swap_b32_e32 v240, v242
	v_permlane16_swap_b32_e32 v241, v243
	s_nop 1
	global_store_dwordx4 v[246:247], v[240:243], off offset:256

; __device__ __forceinline__ unsigned cvt_pk_bf16(float lo, float hi) { unsigned r; asm volatile("v_cvt_pk_bf16_f32 %0, %1, %2" : "=v"(r) : "v"(lo), "v"(hi)); return r; }
;     __device__ __forceinline__ void operator()(f32x4 (&acc)[2][2][4][2], const Unit& u, int wr, int wc, int fr, int fq) const {
;     ...
;                         const unsigned long long wb = wbv[m][bj][n];
;                         f32x4 eb;
;                         eb[0] = __expf(-fmaxf(__uint_as_float((unsigned)(wb & 0xffffull) << 16), -60.f)); eb[1] = __expf(-fmaxf(__uint_as_float((unsigned)((wb >> 16) & 0xffffull) << 16), -60.f));
;                         eb[2] = __expf(-fmaxf(__uint_as_float((unsigned)((wb >> 32) & 0xffffull) << 16), -60.f)); eb[3] = __expf(-fmaxf(__uint_as_float((unsigned)((wb >> 48) & 0xffffull) << 16), -60.f));
;                         if (u.kh == 0) {
;                             const unsigned long long wa = wav[m][bj][n];
;                             f32x4 ea;
;                             ea[0] = __expf(-__uint_as_float((unsigned)(wa & 0xffffull) << 16)); ea[1] = __expf(-__uint_as_float((unsigned)((wa >> 16) & 0xffffull) << 16));
;                             ea[2] = __expf(-__uint_as_float((unsigned)((wa >> 32) & 0xffffull) << 16)); ea[3] = __expf(-__uint_as_float((unsigned)((wa >> 48) & 0xffffull) << 16));
; #pragma unroll
;                             for (int e_ = 0; e_ < 4; ++e_) acc[ai][bj][m][n][e_] *= (1.0f + eb[e_]) * __builtin_amdgcn_rcpf(1.0f + ea[e_]);
;                         } else {
;                             f32x4 o;
; #pragma unroll
;                             for (int e_ = 0; e_ < 4; ++e_) o[e_] = acc[ai][bj][m][n][e_] * __builtin_amdgcn_rcpf(1.0f + eb[e_]);
;                             *(unsigned long long*)(merged + off + bj * HALF + 16 * n) = (unsigned long long)cvt_pk_bf16(o[0], o[1]) | ((unsigned long long)cvt_pk_bf16(o[2], o[3]) << 32);
.LBB0_963:
	v_lshlrev_b32_e32 v1, 16, v180
	v_max_f32_e32 v1, v1, v1
	v_max_f32_e32 v1, 0xc2700000, v1
	v_mul_f32_e32 v1, 0xbfb8aa3b, v1
	v_lshlrev_b64 v[186:187], 11, v[182:183]
	v_exp_f32_e32 v182, v1
	v_and_b32_e32 v1, 0xffff0000, v180
	v_max_f32_e32 v1, v1, v1
	v_max_f32_e32 v1, 0xc2700000, v1
	v_mul_f32_e32 v1, 0xbfb8aa3b, v1
	v_exp_f32_e32 v183, v1
	v_alignbit_b32 v1, v181, v180, 16
	v_and_b32_e32 v1, 0xffff0000, v1
	v_max_f32_e32 v1, v1, v1
	v_max_f32_e32 v1, 0xc2700000, v1
	v_mul_f32_e32 v1, 0xbfb8aa3b, v1
	v_exp_f32_e32 v184, v1
	v_and_b32_e32 v1, 0xffff0000, v181
	v_max_f32_e32 v1, v1, v1
	v_max_f32_e32 v1, 0xc2700000, v1
	v_mul_f32_e32 v1, 0xbfb8aa3b, v1
	v_exp_f32_e32 v185, v1
	v_lshl_add_u64 v[180:181], s[14:15], 0, v[186:187]
	s_mov_b64 s[38:39], -1
	s_and_b64 vcc, exec, s[4:5]
	v_lshl_add_u64 v[180:181], v[2:3], 1, v[180:181]
	s_cbranch_vccnz .LBB0_965
	v_add_f32_e32 v187, 1.0, v185
	v_add_f32_e32 v1, 1.0, v182
	v_add_f32_e32 v145, 1.0, v183
	v_add_f32_e32 v186, 1.0, v184
	v_rcp_f32_e32 v187, v187
	v_rcp_f32_e32 v1, v1
	v_rcp_f32_e32 v145, v145
	v_rcp_f32_e32 v186, v186
	v_mul_f32_e32 v187, v115, v187
	s_mov_b64 s[38:39], 0
	v_mul_f32_e32 v1, v112, v1
	v_mul_f32_e32 v145, v113, v145
	v_mul_f32_e32 v188, v114, v186
	v_cvt_pk_bf16_f32 v186, v1, v145
	v_cvt_pk_bf16_f32 v187, v188, v187
	v_and_b32_e32 v244, 48, v254
	v_mov_b32_e32 v245, 0
	v_lshrrev_b32_e32 v244, 1, v244
	v_mov_b32_e32 v240, v186
	v_mov_b32_e32 v241, v187

; __device__ __forceinline__ unsigned cvt_pk_bf16(float lo, float hi) { unsigned r; asm volatile("v_cvt_pk_bf16_f32 %0, %1, %2" : "=v"(r) : "v"(lo), "v"(hi)); return r; }
;     __device__ __forceinline__ void operator()(f32x4 (&acc)[2][2][4][2], const Unit& u, int wr, int wc, int fr, int fq) const {
;     ...
;                         const unsigned long long wb = wbv[m][bj][n];
;                         f32x4 eb;
;                         eb[0] = __expf(-fmaxf(__uint_as_float((unsigned)(wb & 0xffffull) << 16), -60.f)); eb[1] = __expf(-fmaxf(__uint_as_float((unsigned)((wb >> 16) & 0xffffull) << 16), -60.f));
;                         eb[2] = __expf(-fmaxf(__uint_as_float((unsigned)((wb >> 32) & 0xffffull) << 16), -60.f)); eb[3] = __expf(-fmaxf(__uint_as_float((unsigned)((wb >> 48) & 0xffffull) << 16), -60.f));
;                         if (u.kh == 0) {
;                             const unsigned long long wa = wav[m][bj][n];
;                             f32x4 ea;
;                             ea[0] = __expf(-__uint_as_float((unsigned)(wa & 0xffffull) << 16)); ea[1] = __expf(-__uint_as_float((unsigned)((wa >> 16) & 0xffffull) << 16));
;                             ea[2] = __expf(-__uint_as_float((unsigned)((wa >> 32) & 0xffffull) << 16)); ea[3] = __expf(-__uint_as_float((unsigned)((wa >> 48) & 0xffffull) << 16));
; #pragma unroll
;                             for (int e_ = 0; e_ < 4; ++e_) acc[ai][bj][m][n][e_] *= (1.0f + eb[e_]) * __builtin_amdgcn_rcpf(1.0f + ea[e_]);
;                         } else {
;                             f32x4 o;
; #pragma unroll
;                             for (int e_ = 0; e_ < 4; ++e_) o[e_] = acc[ai][bj][m][n][e_] * __builtin_amdgcn_rcpf(1.0f + eb[e_]);
;                             *(unsigned long long*)(merged + off + bj * HALF + 16 * n) = (unsigned long long)cvt_pk_bf16(o[0], o[1]) | ((unsigned long long)cvt_pk_bf16(o[2], o[3]) << 32);
.LBB0_967:
	v_lshlrev_b32_e32 v1, 16, v176
	v_max_f32_e32 v1, v1, v1
	v_max_f32_e32 v1, 0xc2700000, v1
	v_mul_f32_e32 v1, 0xbfb8aa3b, v1
	v_exp_f32_e32 v178, v1
	v_and_b32_e32 v1, 0xffff0000, v176
	v_max_f32_e32 v1, v1, v1
	v_max_f32_e32 v1, 0xc2700000, v1
	v_mul_f32_e32 v1, 0xbfb8aa3b, v1
	v_exp_f32_e32 v179, v1
	v_alignbit_b32 v1, v177, v176, 16
	v_and_b32_e32 v1, 0xffff0000, v1
	v_max_f32_e32 v1, v1, v1
	v_max_f32_e32 v1, 0xc2700000, v1
	v_mul_f32_e32 v1, 0xbfb8aa3b, v1
	v_exp_f32_e32 v176, v1
	v_and_b32_e32 v1, 0xffff0000, v177
	v_max_f32_e32 v1, v1, v1
	v_max_f32_e32 v1, 0xc2700000, v1
	v_mul_f32_e32 v1, 0xbfb8aa3b, v1
	v_exp_f32_e32 v177, v1
	s_and_b64 vcc, exec, s[4:5]
	s_mov_b64 s[38:39], -1
	s_cbranch_vccnz .LBB0_969
	v_add_f32_e32 v183, 1.0, v177
	v_add_f32_e32 v1, 1.0, v178
	v_add_f32_e32 v145, 1.0, v179
	v_add_f32_e32 v182, 1.0, v176
	v_rcp_f32_e32 v183, v183
	v_rcp_f32_e32 v1, v1
	v_rcp_f32_e32 v145, v145
	v_rcp_f32_e32 v182, v182
	v_mul_f32_e32 v183, v111, v183
	s_mov_b64 s[38:39], 0
	v_mul_f32_e32 v1, v108, v1
	v_mul_f32_e32 v145, v109, v145
	v_mul_f32_e32 v184, v110, v182
	v_cvt_pk_bf16_f32 v182, v1, v145
	v_cvt_pk_bf16_f32 v183, v184, v183
	v_mov_b32_e32 v242, v182
	v_mov_b32_e32 v243, v183
	v_lshl_add_u64 v[246:247], v[180:181], 0, v[244:245]
	s_nop 0
	v_permlane32_swap_b32_e32 v240, v242
	v_permlane32_swap_b32_e32 v241, v243
	s_nop 0
	v_permlane16_swap_b32_e32 v240, v242
	v_permlane16_swap_b32_e32 v241, v243
	s_nop 1
	global_store_dwordx4 v[246:247], v[240:243], off

; __device__ __forceinline__ unsigned cvt_pk_bf16(float lo, float hi) { unsigned r; asm volatile("v_cvt_pk_bf16_f32 %0, %1, %2" : "=v"(r) : "v"(lo), "v"(hi)); return r; }
;     __device__ __forceinline__ void operator()(f32x4 (&acc)[2][2][4][2], const Unit& u, int wr, int wc, int fr, int fq) const {
;     ...
;                         const unsigned long long wb = wbv[m][bj][n];
;                         f32x4 eb;
;                         eb[0] = __expf(-fmaxf(__uint_as_float((unsigned)(wb & 0xffffull) << 16), -60.f)); eb[1] = __expf(-fmaxf(__uint_as_float((unsigned)((wb >> 16) & 0xffffull) << 16), -60.f));
;                         eb[2] = __expf(-fmaxf(__uint_as_float((unsigned)((wb >> 32) & 0xffffull) << 16), -60.f)); eb[3] = __expf(-fmaxf(__uint_as_float((unsigned)((wb >> 48) & 0xffffull) << 16), -60.f));
;                         if (u.kh == 0) {
;                             const unsigned long long wa = wav[m][bj][n];
;                             f32x4 ea;
;                             ea[0] = __expf(-__uint_as_float((unsigned)(wa & 0xffffull) << 16)); ea[1] = __expf(-__uint_as_float((unsigned)((wa >> 16) & 0xffffull) << 16));
;                             ea[2] = __expf(-__uint_as_float((unsigned)((wa >> 32) & 0xffffull) << 16)); ea[3] = __expf(-__uint_as_float((unsigned)((wa >> 48) & 0xffffull) << 16));
; #pragma unroll
;                             for (int e_ = 0; e_ < 4; ++e_) acc[ai][bj][m][n][e_] *= (1.0f + eb[e_]) * __builtin_amdgcn_rcpf(1.0f + ea[e_]);
;                         } else {
;                             f32x4 o;
; #pragma unroll
;                             for (int e_ = 0; e_ < 4; ++e_) o[e_] = acc[ai][bj][m][n][e_] * __builtin_amdgcn_rcpf(1.0f + eb[e_]);
;                             *(unsigned long long*)(merged + off + bj * HALF + 16 * n) = (unsigned long long)cvt_pk_bf16(o[0], o[1]) | ((unsigned long long)cvt_pk_bf16(o[2], o[3]) << 32);
.LBB0_971:
	v_lshlrev_b32_e32 v1, 16, v172
	v_max_f32_e32 v1, v1, v1
	v_max_f32_e32 v1, 0xc2700000, v1
	v_mul_f32_e32 v1, 0xbfb8aa3b, v1
	v_exp_f32_e32 v174, v1
	v_and_b32_e32 v1, 0xffff0000, v172
	v_max_f32_e32 v1, v1, v1
	v_max_f32_e32 v1, 0xc2700000, v1
	v_mul_f32_e32 v1, 0xbfb8aa3b, v1
	v_exp_f32_e32 v175, v1
	v_alignbit_b32 v1, v173, v172, 16
	v_and_b32_e32 v1, 0xffff0000, v1
	v_max_f32_e32 v1, v1, v1
	v_max_f32_e32 v1, 0xc2700000, v1
	v_mul_f32_e32 v1, 0xbfb8aa3b, v1
	v_exp_f32_e32 v172, v1
	v_and_b32_e32 v1, 0xffff0000, v173
	v_max_f32_e32 v1, v1, v1
	v_max_f32_e32 v1, 0xc2700000, v1
	v_mul_f32_e32 v1, 0xbfb8aa3b, v1
	v_exp_f32_e32 v173, v1
	s_and_b64 vcc, exec, s[4:5]
	s_mov_b64 s[38:39], -1
	s_cbranch_vccnz .LBB0_973
	v_add_f32_e32 v177, 1.0, v173
	v_add_f32_e32 v1, 1.0, v174
	v_add_f32_e32 v145, 1.0, v175
	v_add_f32_e32 v176, 1.0, v172
	v_rcp_f32_e32 v177, v177
	v_rcp_f32_e32 v1, v1
	v_rcp_f32_e32 v145, v145
	v_rcp_f32_e32 v176, v176
	v_mul_f32_e32 v177, v83, v177
	s_mov_b64 s[38:39], 0
	v_mul_f32_e32 v1, v80, v1
	v_mul_f32_e32 v145, v81, v145
	v_mul_f32_e32 v178, v82, v176
	v_cvt_pk_bf16_f32 v176, v1, v145
	v_cvt_pk_bf16_f32 v177, v178, v177
	v_mov_b32_e32 v240, v176
	v_mov_b32_e32 v241, v177

; __device__ __forceinline__ unsigned cvt_pk_bf16(float lo, float hi) { unsigned r; asm volatile("v_cvt_pk_bf16_f32 %0, %1, %2" : "=v"(r) : "v"(lo), "v"(hi)); return r; }
;     __device__ __forceinline__ void operator()(f32x4 (&acc)[2][2][4][2], const Unit& u, int wr, int wc, int fr, int fq) const {
;     ...
;                         const unsigned long long wb = wbv[m][bj][n];
;                         f32x4 eb;
;                         eb[0] = __expf(-fmaxf(__uint_as_float((unsigned)(wb & 0xffffull) << 16), -60.f)); eb[1] = __expf(-fmaxf(__uint_as_float((unsigned)((wb >> 16) & 0xffffull) << 16), -60.f));
;                         eb[2] = __expf(-fmaxf(__uint_as_float((unsigned)((wb >> 32) & 0xffffull) << 16), -60.f)); eb[3] = __expf(-fmaxf(__uint_as_float((unsigned)((wb >> 48) & 0xffffull) << 16), -60.f));
;                         if (u.kh == 0) {
;                             const unsigned long long wa = wav[m][bj][n];
;                             f32x4 ea;
;                             ea[0] = __expf(-__uint_as_float((unsigned)(wa & 0xffffull) << 16)); ea[1] = __expf(-__uint_as_float((unsigned)((wa >> 16) & 0xffffull) << 16));
;                             ea[2] = __expf(-__uint_as_float((unsigned)((wa >> 32) & 0xffffull) << 16)); ea[3] = __expf(-__uint_as_float((unsigned)((wa >> 48) & 0xffffull) << 16));
; #pragma unroll
;                             for (int e_ = 0; e_ < 4; ++e_) acc[ai][bj][m][n][e_] *= (1.0f + eb[e_]) * __builtin_amdgcn_rcpf(1.0f + ea[e_]);
;                         } else {
;                             f32x4 o;
; #pragma unroll
;                             for (int e_ = 0; e_ < 4; ++e_) o[e_] = acc[ai][bj][m][n][e_] * __builtin_amdgcn_rcpf(1.0f + eb[e_]);
;                             *(unsigned long long*)(merged + off + bj * HALF + 16 * n) = (unsigned long long)cvt_pk_bf16(o[0], o[1]) | ((unsigned long long)cvt_pk_bf16(o[2], o[3]) << 32);
.LBB0_975:
	v_lshlrev_b32_e32 v1, 16, v168
	v_max_f32_e32 v1, v1, v1
	v_max_f32_e32 v1, 0xc2700000, v1
	v_mul_f32_e32 v1, 0xbfb8aa3b, v1
	v_exp_f32_e32 v170, v1
	v_and_b32_e32 v1, 0xffff0000, v168
	v_max_f32_e32 v1, v1, v1
	v_max_f32_e32 v1, 0xc2700000, v1
	v_mul_f32_e32 v1, 0xbfb8aa3b, v1
	v_exp_f32_e32 v171, v1
	v_alignbit_b32 v1, v169, v168, 16
	v_and_b32_e32 v1, 0xffff0000, v1
	v_max_f32_e32 v1, v1, v1
	v_max_f32_e32 v1, 0xc2700000, v1
	v_mul_f32_e32 v1, 0xbfb8aa3b, v1
	v_exp_f32_e32 v168, v1
	v_and_b32_e32 v1, 0xffff0000, v169
	v_max_f32_e32 v1, v1, v1
	v_max_f32_e32 v1, 0xc2700000, v1
	v_mul_f32_e32 v1, 0xbfb8aa3b, v1
	v_exp_f32_e32 v169, v1
	s_and_b64 vcc, exec, s[4:5]
	s_mov_b64 s[38:39], -1
	s_cbranch_vccnz .LBB0_977
	v_add_f32_e32 v173, 1.0, v169
	v_add_f32_e32 v1, 1.0, v170
	v_add_f32_e32 v145, 1.0, v171
	v_add_f32_e32 v172, 1.0, v168
	v_rcp_f32_e32 v173, v173
	v_rcp_f32_e32 v1, v1
	v_rcp_f32_e32 v145, v145
	v_rcp_f32_e32 v172, v172
	v_mul_f32_e32 v173, v79, v173
	s_mov_b64 s[38:39], 0
	v_mul_f32_e32 v1, v76, v1
	v_mul_f32_e32 v145, v77, v145
	v_mul_f32_e32 v174, v78, v172
	v_cvt_pk_bf16_f32 v172, v1, v145
	v_cvt_pk_bf16_f32 v173, v174, v173
	v_mov_b32_e32 v242, v172
	v_mov_b32_e32 v243, v173
	v_lshl_add_u64 v[246:247], v[180:181], 0, v[244:245]
	s_nop 0
	v_permlane32_swap_b32_e32 v240, v242
	v_permlane32_swap_b32_e32 v241, v243
	s_nop 0
	v_permlane16_swap_b32_e32 v240, v242
	v_permlane16_swap_b32_e32 v241, v243
	s_nop 1
	global_store_dwordx4 v[246:247], v[240:243], off offset:256

; __device__ __forceinline__ unsigned cvt_pk_bf16(float lo, float hi) { unsigned r; asm volatile("v_cvt_pk_bf16_f32 %0, %1, %2" : "=v"(r) : "v"(lo), "v"(hi)); return r; }
;     __device__ __forceinline__ void operator()(f32x4 (&acc)[2][2][4][2], const Unit& u, int wr, int wc, int fr, int fq) const {
;     ...
;                         const unsigned long long wb = wbv[m][bj][n];
;                         f32x4 eb;
;                         eb[0] = __expf(-fmaxf(__uint_as_float((unsigned)(wb & 0xffffull) << 16), -60.f)); eb[1] = __expf(-fmaxf(__uint_as_float((unsigned)((wb >> 16) & 0xffffull) << 16), -60.f));
;                         eb[2] = __expf(-fmaxf(__uint_as_float((unsigned)((wb >> 32) & 0xffffull) << 16), -60.f)); eb[3] = __expf(-fmaxf(__uint_as_float((unsigned)((wb >> 48) & 0xffffull) << 16), -60.f));
;                         if (u.kh == 0) {
;                             const unsigned long long wa = wav[m][bj][n];
;                             f32x4 ea;
;                             ea[0] = __expf(-__uint_as_float((unsigned)(wa & 0xffffull) << 16)); ea[1] = __expf(-__uint_as_float((unsigned)((wa >> 16) & 0xffffull) << 16));
;                             ea[2] = __expf(-__uint_as_float((unsigned)((wa >> 32) & 0xffffull) << 16)); ea[3] = __expf(-__uint_as_float((unsigned)((wa >> 48) & 0xffffull) << 16));
; #pragma unroll
;                             for (int e_ = 0; e_ < 4; ++e_) acc[ai][bj][m][n][e_] *= (1.0f + eb[e_]) * __builtin_amdgcn_rcpf(1.0f + ea[e_]);
;                         } else {
;                             f32x4 o;
; #pragma unroll
;                             for (int e_ = 0; e_ < 4; ++e_) o[e_] = acc[ai][bj][m][n][e_] * __builtin_amdgcn_rcpf(1.0f + eb[e_]);
;                             *(unsigned long long*)(merged + off + bj * HALF + 16 * n) = (unsigned long long)cvt_pk_bf16(o[0], o[1]) | ((unsigned long long)cvt_pk_bf16(o[2], o[3]) << 32);
.LBB0_979:
	v_lshlrev_b32_e32 v1, 16, v162
	v_max_f32_e32 v1, v1, v1
	v_max_f32_e32 v1, 0xc2700000, v1
	v_mul_f32_e32 v1, 0xbfb8aa3b, v1
	v_lshlrev_b64 v[168:169], 11, v[164:165]
	v_exp_f32_e32 v164, v1
	v_and_b32_e32 v1, 0xffff0000, v162
	v_max_f32_e32 v1, v1, v1
	v_max_f32_e32 v1, 0xc2700000, v1
	v_mul_f32_e32 v1, 0xbfb8aa3b, v1
	v_exp_f32_e32 v165, v1
	v_alignbit_b32 v1, v163, v162, 16
	v_and_b32_e32 v1, 0xffff0000, v1
	v_max_f32_e32 v1, v1, v1
	v_max_f32_e32 v1, 0xc2700000, v1
	v_mul_f32_e32 v1, 0xbfb8aa3b, v1
	v_exp_f32_e32 v166, v1
	v_and_b32_e32 v1, 0xffff0000, v163
	v_max_f32_e32 v1, v1, v1
	v_max_f32_e32 v1, 0xc2700000, v1
	v_mul_f32_e32 v1, 0xbfb8aa3b, v1
	v_exp_f32_e32 v167, v1
	v_lshl_add_u64 v[162:163], s[14:15], 0, v[168:169]
	s_mov_b64 s[38:39], -1
	s_and_b64 vcc, exec, s[4:5]
	v_lshl_add_u64 v[162:163], v[2:3], 1, v[162:163]
	s_cbranch_vccnz .LBB0_981
	v_add_f32_e32 v169, 1.0, v167
	v_add_f32_e32 v1, 1.0, v164
	v_add_f32_e32 v145, 1.0, v165
	v_add_f32_e32 v168, 1.0, v166
	v_rcp_f32_e32 v169, v169
	v_rcp_f32_e32 v1, v1
	v_rcp_f32_e32 v145, v145
	v_rcp_f32_e32 v168, v168
	v_mul_f32_e32 v169, v107, v169
	s_mov_b64 s[38:39], 0
	v_mul_f32_e32 v1, v104, v1
	v_mul_f32_e32 v145, v105, v145
	v_mul_f32_e32 v170, v106, v168
	v_cvt_pk_bf16_f32 v168, v1, v145
	v_cvt_pk_bf16_f32 v169, v170, v169
	v_and_b32_e32 v244, 48, v254
	v_mov_b32_e32 v245, 0
	v_lshrrev_b32_e32 v244, 1, v244
	v_mov_b32_e32 v240, v168
	v_mov_b32_e32 v241, v169

; __device__ __forceinline__ unsigned cvt_pk_bf16(float lo, float hi) { unsigned r; asm volatile("v_cvt_pk_bf16_f32 %0, %1, %2" : "=v"(r) : "v"(lo), "v"(hi)); return r; }
;     __device__ __forceinline__ void operator()(f32x4 (&acc)[2][2][4][2], const Unit& u, int wr, int wc, int fr, int fq) const {
;     ...
;                         const unsigned long long wb = wbv[m][bj][n];
;                         f32x4 eb;
;                         eb[0] = __expf(-fmaxf(__uint_as_float((unsigned)(wb & 0xffffull) << 16), -60.f)); eb[1] = __expf(-fmaxf(__uint_as_float((unsigned)((wb >> 16) & 0xffffull) << 16), -60.f));
;                         eb[2] = __expf(-fmaxf(__uint_as_float((unsigned)((wb >> 32) & 0xffffull) << 16), -60.f)); eb[3] = __expf(-fmaxf(__uint_as_float((unsigned)((wb >> 48) & 0xffffull) << 16), -60.f));
;                         if (u.kh == 0) {
;                             const unsigned long long wa = wav[m][bj][n];
;                             f32x4 ea;
;                             ea[0] = __expf(-__uint_as_float((unsigned)(wa & 0xffffull) << 16)); ea[1] = __expf(-__uint_as_float((unsigned)((wa >> 16) & 0xffffull) << 16));
;                             ea[2] = __expf(-__uint_as_float((unsigned)((wa >> 32) & 0xffffull) << 16)); ea[3] = __expf(-__uint_as_float((unsigned)((wa >> 48) & 0xffffull) << 16));
; #pragma unroll
;                             for (int e_ = 0; e_ < 4; ++e_) acc[ai][bj][m][n][e_] *= (1.0f + eb[e_]) * __builtin_amdgcn_rcpf(1.0f + ea[e_]);
;                         } else {
;                             f32x4 o;
; #pragma unroll
;                             for (int e_ = 0; e_ < 4; ++e_) o[e_] = acc[ai][bj][m][n][e_] * __builtin_amdgcn_rcpf(1.0f + eb[e_]);
;                             *(unsigned long long*)(merged + off + bj * HALF + 16 * n) = (unsigned long long)cvt_pk_bf16(o[0], o[1]) | ((unsigned long long)cvt_pk_bf16(o[2], o[3]) << 32);
.LBB0_983:
	v_lshlrev_b32_e32 v1, 16, v158
	v_max_f32_e32 v1, v1, v1
	v_max_f32_e32 v1, 0xc2700000, v1
	v_mul_f32_e32 v1, 0xbfb8aa3b, v1
	v_exp_f32_e32 v160, v1
	v_and_b32_e32 v1, 0xffff0000, v158
	v_max_f32_e32 v1, v1, v1
	v_max_f32_e32 v1, 0xc2700000, v1
	v_mul_f32_e32 v1, 0xbfb8aa3b, v1
	v_exp_f32_e32 v161, v1
	v_alignbit_b32 v1, v159, v158, 16
	v_and_b32_e32 v1, 0xffff0000, v1
	v_max_f32_e32 v1, v1, v1
	v_max_f32_e32 v1, 0xc2700000, v1
	v_mul_f32_e32 v1, 0xbfb8aa3b, v1
	v_exp_f32_e32 v158, v1
	v_and_b32_e32 v1, 0xffff0000, v159
	v_max_f32_e32 v1, v1, v1
	v_max_f32_e32 v1, 0xc2700000, v1
	v_mul_f32_e32 v1, 0xbfb8aa3b, v1
	v_exp_f32_e32 v159, v1
	s_and_b64 vcc, exec, s[4:5]
	s_mov_b64 s[38:39], -1
	s_cbranch_vccnz .LBB0_985
	v_add_f32_e32 v165, 1.0, v159
	v_add_f32_e32 v1, 1.0, v160
	v_add_f32_e32 v145, 1.0, v161
	v_add_f32_e32 v164, 1.0, v158
	v_rcp_f32_e32 v165, v165
	v_rcp_f32_e32 v1, v1
	v_rcp_f32_e32 v145, v145
	v_rcp_f32_e32 v164, v164
	v_mul_f32_e32 v165, v103, v165
	s_mov_b64 s[38:39], 0
	v_mul_f32_e32 v1, v100, v1
	v_mul_f32_e32 v145, v101, v145
	v_mul_f32_e32 v166, v102, v164
	v_cvt_pk_bf16_f32 v164, v1, v145
	v_cvt_pk_bf16_f32 v165, v166, v165
	v_mov_b32_e32 v242, v164
	v_mov_b32_e32 v243, v165
	v_lshl_add_u64 v[246:247], v[162:163], 0, v[244:245]
	s_nop 0
	v_permlane32_swap_b32_e32 v240, v242
	v_permlane32_swap_b32_e32 v241, v243
	s_nop 0
	v_permlane16_swap_b32_e32 v240, v242
	v_permlane16_swap_b32_e32 v241, v243
	s_nop 1
	global_store_dwordx4 v[246:247], v[240:243], off

; __device__ __forceinline__ unsigned cvt_pk_bf16(float lo, float hi) { unsigned r; asm volatile("v_cvt_pk_bf16_f32 %0, %1, %2" : "=v"(r) : "v"(lo), "v"(hi)); return r; }
;     __device__ __forceinline__ void operator()(f32x4 (&acc)[2][2][4][2], const Unit& u, int wr, int wc, int fr, int fq) const {
;     ...
;                         const unsigned long long wb = wbv[m][bj][n];
;                         f32x4 eb;
;                         eb[0] = __expf(-fmaxf(__uint_as_float((unsigned)(wb & 0xffffull) << 16), -60.f)); eb[1] = __expf(-fmaxf(__uint_as_float((unsigned)((wb >> 16) & 0xffffull) << 16), -60.f));
;                         eb[2] = __expf(-fmaxf(__uint_as_float((unsigned)((wb >> 32) & 0xffffull) << 16), -60.f)); eb[3] = __expf(-fmaxf(__uint_as_float((unsigned)((wb >> 48) & 0xffffull) << 16), -60.f));
;                         if (u.kh == 0) {
;                             const unsigned long long wa = wav[m][bj][n];
;                             f32x4 ea;
;                             ea[0] = __expf(-__uint_as_float((unsigned)(wa & 0xffffull) << 16)); ea[1] = __expf(-__uint_as_float((unsigned)((wa >> 16) & 0xffffull) << 16));
;                             ea[2] = __expf(-__uint_as_float((unsigned)((wa >> 32) & 0xffffull) << 16)); ea[3] = __expf(-__uint_as_float((unsigned)((wa >> 48) & 0xffffull) << 16));
; #pragma unroll
;                             for (int e_ = 0; e_ < 4; ++e_) acc[ai][bj][m][n][e_] *= (1.0f + eb[e_]) * __builtin_amdgcn_rcpf(1.0f + ea[e_]);
;                         } else {
;                             f32x4 o;
; #pragma unroll
;                             for (int e_ = 0; e_ < 4; ++e_) o[e_] = acc[ai][bj][m][n][e_] * __builtin_amdgcn_rcpf(1.0f + eb[e_]);
;                             *(unsigned long long*)(merged + off + bj * HALF + 16 * n) = (unsigned long long)cvt_pk_bf16(o[0], o[1]) | ((unsigned long long)cvt_pk_bf16(o[2], o[3]) << 32);
.LBB0_987:
	v_lshlrev_b32_e32 v1, 16, v154
	v_max_f32_e32 v1, v1, v1
	v_max_f32_e32 v1, 0xc2700000, v1
	v_mul_f32_e32 v1, 0xbfb8aa3b, v1
	v_exp_f32_e32 v156, v1
	v_and_b32_e32 v1, 0xffff0000, v154
	v_max_f32_e32 v1, v1, v1
	v_max_f32_e32 v1, 0xc2700000, v1
	v_mul_f32_e32 v1, 0xbfb8aa3b, v1
	v_exp_f32_e32 v157, v1
	v_alignbit_b32 v1, v155, v154, 16
	v_and_b32_e32 v1, 0xffff0000, v1
	v_max_f32_e32 v1, v1, v1
	v_max_f32_e32 v1, 0xc2700000, v1
	v_mul_f32_e32 v1, 0xbfb8aa3b, v1
	v_exp_f32_e32 v154, v1
	v_and_b32_e32 v1, 0xffff0000, v155
	v_max_f32_e32 v1, v1, v1
	v_max_f32_e32 v1, 0xc2700000, v1
	v_mul_f32_e32 v1, 0xbfb8aa3b, v1
	v_exp_f32_e32 v155, v1
	s_and_b64 vcc, exec, s[4:5]
	s_mov_b64 s[38:39], -1
	s_cbranch_vccnz .LBB0_989
	v_add_f32_e32 v159, 1.0, v155
	v_add_f32_e32 v1, 1.0, v156
	v_add_f32_e32 v145, 1.0, v157
	v_add_f32_e32 v158, 1.0, v154
	v_rcp_f32_e32 v159, v159
	v_rcp_f32_e32 v1, v1
	v_rcp_f32_e32 v145, v145
	v_rcp_f32_e32 v158, v158
	v_mul_f32_e32 v159, v75, v159
	s_mov_b64 s[38:39], 0
	v_mul_f32_e32 v1, v72, v1
	v_mul_f32_e32 v145, v73, v145
	v_mul_f32_e32 v160, v74, v158
	v_cvt_pk_bf16_f32 v158, v1, v145
	v_cvt_pk_bf16_f32 v159, v160, v159
	v_mov_b32_e32 v240, v158
	v_mov_b32_e32 v241, v159

; __device__ __forceinline__ unsigned cvt_pk_bf16(float lo, float hi) { unsigned r; asm volatile("v_cvt_pk_bf16_f32 %0, %1, %2" : "=v"(r) : "v"(lo), "v"(hi)); return r; }
;     __device__ __forceinline__ void operator()(f32x4 (&acc)[2][2][4][2], const Unit& u, int wr, int wc, int fr, int fq) const {
;     ...
;                         const unsigned long long wb = wbv[m][bj][n];
;                         f32x4 eb;
;                         eb[0] = __expf(-fmaxf(__uint_as_float((unsigned)(wb & 0xffffull) << 16), -60.f)); eb[1] = __expf(-fmaxf(__uint_as_float((unsigned)((wb >> 16) & 0xffffull) << 16), -60.f));
;                         eb[2] = __expf(-fmaxf(__uint_as_float((unsigned)((wb >> 32) & 0xffffull) << 16), -60.f)); eb[3] = __expf(-fmaxf(__uint_as_float((unsigned)((wb >> 48) & 0xffffull) << 16), -60.f));
;                         if (u.kh == 0) {
;                             const unsigned long long wa = wav[m][bj][n];
;                             f32x4 ea;
;                             ea[0] = __expf(-__uint_as_float((unsigned)(wa & 0xffffull) << 16)); ea[1] = __expf(-__uint_as_float((unsigned)((wa >> 16) & 0xffffull) << 16));
;                             ea[2] = __expf(-__uint_as_float((unsigned)((wa >> 32) & 0xffffull) << 16)); ea[3] = __expf(-__uint_as_float((unsigned)((wa >> 48) & 0xffffull) << 16));
; #pragma unroll
;                             for (int e_ = 0; e_ < 4; ++e_) acc[ai][bj][m][n][e_] *= (1.0f + eb[e_]) * __builtin_amdgcn_rcpf(1.0f + ea[e_]);
;                         } else {
;                             f32x4 o;
; #pragma unroll
;                             for (int e_ = 0; e_ < 4; ++e_) o[e_] = acc[ai][bj][m][n][e_] * __builtin_amdgcn_rcpf(1.0f + eb[e_]);
;                             *(unsigned long long*)(merged + off + bj * HALF + 16 * n) = (unsigned long long)cvt_pk_bf16(o[0], o[1]) | ((unsigned long long)cvt_pk_bf16(o[2], o[3]) << 32);
.LBB0_991:
	v_lshlrev_b32_e32 v1, 16, v150
	v_max_f32_e32 v1, v1, v1
	v_max_f32_e32 v1, 0xc2700000, v1
	v_mul_f32_e32 v1, 0xbfb8aa3b, v1
	v_exp_f32_e32 v152, v1
	v_and_b32_e32 v1, 0xffff0000, v150
	v_max_f32_e32 v1, v1, v1
	v_max_f32_e32 v1, 0xc2700000, v1
	v_mul_f32_e32 v1, 0xbfb8aa3b, v1
	v_exp_f32_e32 v153, v1
	v_alignbit_b32 v1, v151, v150, 16
	v_and_b32_e32 v1, 0xffff0000, v1
	v_max_f32_e32 v1, v1, v1
	v_max_f32_e32 v1, 0xc2700000, v1
	v_mul_f32_e32 v1, 0xbfb8aa3b, v1
	v_exp_f32_e32 v150, v1
	v_and_b32_e32 v1, 0xffff0000, v151
	v_max_f32_e32 v1, v1, v1
	v_max_f32_e32 v1, 0xc2700000, v1
	v_mul_f32_e32 v1, 0xbfb8aa3b, v1
	v_exp_f32_e32 v151, v1
	s_and_b64 vcc, exec, s[4:5]
	s_mov_b64 s[38:39], -1
	s_cbranch_vccnz .LBB0_993
	v_add_f32_e32 v155, 1.0, v151
	v_add_f32_e32 v1, 1.0, v152
	v_add_f32_e32 v145, 1.0, v153
	v_add_f32_e32 v154, 1.0, v150
	v_rcp_f32_e32 v155, v155
	v_rcp_f32_e32 v1, v1
	v_rcp_f32_e32 v145, v145
	v_rcp_f32_e32 v154, v154
	v_mul_f32_e32 v155, v71, v155
	s_mov_b64 s[38:39], 0
	v_mul_f32_e32 v1, v68, v1
	v_mul_f32_e32 v145, v69, v145
	v_mul_f32_e32 v156, v70, v154
	v_cvt_pk_bf16_f32 v154, v1, v145
	v_cvt_pk_bf16_f32 v155, v156, v155
	v_mov_b32_e32 v242, v154
	v_mov_b32_e32 v243, v155
	v_lshl_add_u64 v[246:247], v[162:163], 0, v[244:245]
	s_nop 0
	v_permlane32_swap_b32_e32 v240, v242
	v_permlane32_swap_b32_e32 v241, v243
	s_nop 0
	v_permlane16_swap_b32_e32 v240, v242
	v_permlane16_swap_b32_e32 v241, v243
	s_nop 1
	global_store_dwordx4 v[246:247], v[240:243], off offset:256

; __device__ __forceinline__ unsigned cvt_pk_bf16(float lo, float hi) { unsigned r; asm volatile("v_cvt_pk_bf16_f32 %0, %1, %2" : "=v"(r) : "v"(lo), "v"(hi)); return r; }
;     __device__ __forceinline__ void operator()(f32x4 (&acc)[2][2][4][2], const Unit& u, int wr, int wc, int fr, int fq) const {
;     ...
;                         const unsigned long long wb = wbv[m][bj][n];
;                         f32x4 eb;
;                         eb[0] = __expf(-fmaxf(__uint_as_float((unsigned)(wb & 0xffffull) << 16), -60.f)); eb[1] = __expf(-fmaxf(__uint_as_float((unsigned)((wb >> 16) & 0xffffull) << 16), -60.f));
;                         eb[2] = __expf(-fmaxf(__uint_as_float((unsigned)((wb >> 32) & 0xffffull) << 16), -60.f)); eb[3] = __expf(-fmaxf(__uint_as_float((unsigned)((wb >> 48) & 0xffffull) << 16), -60.f));
;                         if (u.kh == 0) {
;                             const unsigned long long wa = wav[m][bj][n];
;                             f32x4 ea;
;                             ea[0] = __expf(-__uint_as_float((unsigned)(wa & 0xffffull) << 16)); ea[1] = __expf(-__uint_as_float((unsigned)((wa >> 16) & 0xffffull) << 16));
;                             ea[2] = __expf(-__uint_as_float((unsigned)((wa >> 32) & 0xffffull) << 16)); ea[3] = __expf(-__uint_as_float((unsigned)((wa >> 48) & 0xffffull) << 16));
; #pragma unroll
;                             for (int e_ = 0; e_ < 4; ++e_) acc[ai][bj][m][n][e_] *= (1.0f + eb[e_]) * __builtin_amdgcn_rcpf(1.0f + ea[e_]);
;                         } else {
;                             f32x4 o;
; #pragma unroll
;                             for (int e_ = 0; e_ < 4; ++e_) o[e_] = acc[ai][bj][m][n][e_] * __builtin_amdgcn_rcpf(1.0f + eb[e_]);
;                             *(unsigned long long*)(merged + off + bj * HALF + 16 * n) = (unsigned long long)cvt_pk_bf16(o[0], o[1]) | ((unsigned long long)cvt_pk_bf16(o[2], o[3]) << 32);
.LBB0_1011:
	s_waitcnt vmcnt(15)
	v_lshlrev_b32_e32 v1, 16, v208
	v_max_f32_e32 v1, v1, v1
	v_max_f32_e32 v1, 0xc2700000, v1
	v_mul_f32_e32 v1, 0xbfb8aa3b, v1
	v_lshlrev_b64 v[218:219], 11, v[214:215]
	v_exp_f32_e32 v214, v1
	v_and_b32_e32 v1, 0xffff0000, v208
	v_max_f32_e32 v1, v1, v1
	v_max_f32_e32 v1, 0xc2700000, v1
	v_mul_f32_e32 v1, 0xbfb8aa3b, v1
	v_exp_f32_e32 v215, v1
	v_alignbit_b32 v1, v209, v208, 16
	v_and_b32_e32 v1, 0xffff0000, v1
	v_max_f32_e32 v1, v1, v1
	v_max_f32_e32 v1, 0xc2700000, v1
	v_mul_f32_e32 v1, 0xbfb8aa3b, v1
	v_exp_f32_e32 v216, v1
	v_and_b32_e32 v1, 0xffff0000, v209
	v_max_f32_e32 v1, v1, v1
	v_max_f32_e32 v1, 0xc2700000, v1
	v_mul_f32_e32 v1, 0xbfb8aa3b, v1
	v_exp_f32_e32 v217, v1
	v_lshl_add_u64 v[208:209], s[14:15], 0, v[218:219]
	s_mov_b64 s[6:7], -1
	s_and_b64 vcc, exec, s[4:5]
	v_lshl_add_u64 v[208:209], v[2:3], 1, v[208:209]
	s_cbranch_vccnz .LBB0_1013
	v_add_f32_e32 v218, 1.0, v215
	v_add_f32_e32 v219, 1.0, v216
	v_add_f32_e32 v1, 1.0, v214
	v_rcp_f32_e32 v218, v218
	v_rcp_f32_e32 v219, v219
	v_add_f32_e32 v220, 1.0, v217
	v_rcp_f32_e32 v1, v1
	v_rcp_f32_e32 v220, v220
	v_mul_f32_e32 v218, v65, v218
	v_mul_f32_e32 v219, v66, v219
	s_mov_b64 s[6:7], 0
	v_mul_f32_e32 v1, v64, v1
	v_mul_f32_e32 v220, v67, v220
	v_cvt_pk_bf16_f32 v218, v1, v218
	v_cvt_pk_bf16_f32 v219, v219, v220
	v_and_b32_e32 v244, 48, v254
	v_mov_b32_e32 v245, 0
	v_lshrrev_b32_e32 v244, 1, v244
	v_mov_b32_e32 v240, v218
	v_mov_b32_e32 v241, v219

; __device__ __forceinline__ unsigned cvt_pk_bf16(float lo, float hi) { unsigned r; asm volatile("v_cvt_pk_bf16_f32 %0, %1, %2" : "=v"(r) : "v"(lo), "v"(hi)); return r; }
;     __device__ __forceinline__ void operator()(f32x4 (&acc)[2][2][4][2], const Unit& u, int wr, int wc, int fr, int fq) const {
;     ...
;                         const unsigned long long wb = wbv[m][bj][n];
;                         f32x4 eb;
;                         eb[0] = __expf(-fmaxf(__uint_as_float((unsigned)(wb & 0xffffull) << 16), -60.f)); eb[1] = __expf(-fmaxf(__uint_as_float((unsigned)((wb >> 16) & 0xffffull) << 16), -60.f));
;                         eb[2] = __expf(-fmaxf(__uint_as_float((unsigned)((wb >> 32) & 0xffffull) << 16), -60.f)); eb[3] = __expf(-fmaxf(__uint_as_float((unsigned)((wb >> 48) & 0xffffull) << 16), -60.f));
;                         if (u.kh == 0) {
;                             const unsigned long long wa = wav[m][bj][n];
;                             f32x4 ea;
;                             ea[0] = __expf(-__uint_as_float((unsigned)(wa & 0xffffull) << 16)); ea[1] = __expf(-__uint_as_float((unsigned)((wa >> 16) & 0xffffull) << 16));
;                             ea[2] = __expf(-__uint_as_float((unsigned)((wa >> 32) & 0xffffull) << 16)); ea[3] = __expf(-__uint_as_float((unsigned)((wa >> 48) & 0xffffull) << 16));
; #pragma unroll
;                             for (int e_ = 0; e_ < 4; ++e_) acc[ai][bj][m][n][e_] *= (1.0f + eb[e_]) * __builtin_amdgcn_rcpf(1.0f + ea[e_]);
;                         } else {
;                             f32x4 o;
; #pragma unroll
;                             for (int e_ = 0; e_ < 4; ++e_) o[e_] = acc[ai][bj][m][n][e_] * __builtin_amdgcn_rcpf(1.0f + eb[e_]);
;                             *(unsigned long long*)(merged + off + bj * HALF + 16 * n) = (unsigned long long)cvt_pk_bf16(o[0], o[1]) | ((unsigned long long)cvt_pk_bf16(o[2], o[3]) << 32);
.LBB0_1015:
	s_waitcnt vmcnt(14)
	v_lshlrev_b32_e32 v1, 16, v210
	v_max_f32_e32 v1, v1, v1
	v_max_f32_e32 v1, 0xc2700000, v1
	v_mul_f32_e32 v1, 0xbfb8aa3b, v1
	v_exp_f32_e32 v212, v1
	v_and_b32_e32 v1, 0xffff0000, v210
	v_max_f32_e32 v1, v1, v1
	v_max_f32_e32 v1, 0xc2700000, v1
	v_mul_f32_e32 v1, 0xbfb8aa3b, v1
	v_exp_f32_e32 v213, v1
	v_alignbit_b32 v1, v211, v210, 16
	v_and_b32_e32 v1, 0xffff0000, v1
	v_max_f32_e32 v1, v1, v1
	v_max_f32_e32 v1, 0xc2700000, v1
	v_mul_f32_e32 v1, 0xbfb8aa3b, v1
	v_exp_f32_e32 v210, v1
	v_and_b32_e32 v1, 0xffff0000, v211
	v_max_f32_e32 v1, v1, v1
	v_max_f32_e32 v1, 0xc2700000, v1
	v_mul_f32_e32 v1, 0xbfb8aa3b, v1
	v_exp_f32_e32 v211, v1
	s_and_b64 vcc, exec, s[4:5]
	s_mov_b64 s[6:7], -1
	s_cbranch_vccnz .LBB0_1017
	v_add_f32_e32 v214, 1.0, v213
	v_add_f32_e32 v215, 1.0, v210
	v_add_f32_e32 v1, 1.0, v212
	v_rcp_f32_e32 v214, v214
	v_rcp_f32_e32 v215, v215
	v_add_f32_e32 v216, 1.0, v211
	v_rcp_f32_e32 v1, v1
	v_rcp_f32_e32 v216, v216
	v_mul_f32_e32 v214, v61, v214
	v_mul_f32_e32 v215, v62, v215
	s_mov_b64 s[6:7], 0
	v_mul_f32_e32 v1, v60, v1
	v_mul_f32_e32 v216, v63, v216
	v_cvt_pk_bf16_f32 v214, v1, v214
	v_cvt_pk_bf16_f32 v215, v215, v216
	v_mov_b32_e32 v242, v214
	v_mov_b32_e32 v243, v215
	v_lshl_add_u64 v[246:247], v[208:209], 0, v[244:245]
	s_nop 0
	v_permlane32_swap_b32_e32 v240, v242
	v_permlane32_swap_b32_e32 v241, v243
	s_nop 0
	v_permlane16_swap_b32_e32 v240, v242
	v_permlane16_swap_b32_e32 v241, v243
	s_nop 1
	global_store_dwordx4 v[246:247], v[240:243], off

; __device__ __forceinline__ unsigned cvt_pk_bf16(float lo, float hi) { unsigned r; asm volatile("v_cvt_pk_bf16_f32 %0, %1, %2" : "=v"(r) : "v"(lo), "v"(hi)); return r; }
;     __device__ __forceinline__ void operator()(f32x4 (&acc)[2][2][4][2], const Unit& u, int wr, int wc, int fr, int fq) const {
;     ...
;                         const unsigned long long wb = wbv[m][bj][n];
;                         f32x4 eb;
;                         eb[0] = __expf(-fmaxf(__uint_as_float((unsigned)(wb & 0xffffull) << 16), -60.f)); eb[1] = __expf(-fmaxf(__uint_as_float((unsigned)((wb >> 16) & 0xffffull) << 16), -60.f));
;                         eb[2] = __expf(-fmaxf(__uint_as_float((unsigned)((wb >> 32) & 0xffffull) << 16), -60.f)); eb[3] = __expf(-fmaxf(__uint_as_float((unsigned)((wb >> 48) & 0xffffull) << 16), -60.f));
;                         if (u.kh == 0) {
;                             const unsigned long long wa = wav[m][bj][n];
;                             f32x4 ea;
;                             ea[0] = __expf(-__uint_as_float((unsigned)(wa & 0xffffull) << 16)); ea[1] = __expf(-__uint_as_float((unsigned)((wa >> 16) & 0xffffull) << 16));
;                             ea[2] = __expf(-__uint_as_float((unsigned)((wa >> 32) & 0xffffull) << 16)); ea[3] = __expf(-__uint_as_float((unsigned)((wa >> 48) & 0xffffull) << 16));
; #pragma unroll
;                             for (int e_ = 0; e_ < 4; ++e_) acc[ai][bj][m][n][e_] *= (1.0f + eb[e_]) * __builtin_amdgcn_rcpf(1.0f + ea[e_]);
;                         } else {
;                             f32x4 o;
; #pragma unroll
;                             for (int e_ = 0; e_ < 4; ++e_) o[e_] = acc[ai][bj][m][n][e_] * __builtin_amdgcn_rcpf(1.0f + eb[e_]);
;                             *(unsigned long long*)(merged + off + bj * HALF + 16 * n) = (unsigned long long)cvt_pk_bf16(o[0], o[1]) | ((unsigned long long)cvt_pk_bf16(o[2], o[3]) << 32);
.LBB0_1019:
	s_waitcnt vmcnt(13)
	v_lshlrev_b32_e32 v1, 16, v204
	v_max_f32_e32 v1, v1, v1
	v_max_f32_e32 v1, 0xc2700000, v1
	v_mul_f32_e32 v1, 0xbfb8aa3b, v1
	v_exp_f32_e32 v206, v1
	v_and_b32_e32 v1, 0xffff0000, v204
	v_max_f32_e32 v1, v1, v1
	v_max_f32_e32 v1, 0xc2700000, v1
	v_mul_f32_e32 v1, 0xbfb8aa3b, v1
	v_exp_f32_e32 v207, v1
	v_alignbit_b32 v1, v205, v204, 16
	v_and_b32_e32 v1, 0xffff0000, v1
	v_max_f32_e32 v1, v1, v1
	v_max_f32_e32 v1, 0xc2700000, v1
	v_mul_f32_e32 v1, 0xbfb8aa3b, v1
	v_exp_f32_e32 v204, v1
	v_and_b32_e32 v1, 0xffff0000, v205
	v_max_f32_e32 v1, v1, v1
	v_max_f32_e32 v1, 0xc2700000, v1
	v_mul_f32_e32 v1, 0xbfb8aa3b, v1
	v_exp_f32_e32 v205, v1
	s_and_b64 vcc, exec, s[4:5]
	s_mov_b64 s[6:7], -1
	s_cbranch_vccnz .LBB0_1021
	v_add_f32_e32 v210, 1.0, v207
	v_add_f32_e32 v211, 1.0, v204
	v_add_f32_e32 v1, 1.0, v206
	v_rcp_f32_e32 v210, v210
	v_rcp_f32_e32 v211, v211
	v_add_f32_e32 v212, 1.0, v205
	v_rcp_f32_e32 v1, v1
	v_rcp_f32_e32 v212, v212
	v_mul_f32_e32 v210, v33, v210
	v_mul_f32_e32 v211, v34, v211
	s_mov_b64 s[6:7], 0
	v_mul_f32_e32 v1, v32, v1
	v_mul_f32_e32 v212, v35, v212
	v_cvt_pk_bf16_f32 v210, v1, v210
	v_cvt_pk_bf16_f32 v211, v211, v212
	v_mov_b32_e32 v240, v210
	v_mov_b32_e32 v241, v211

; __device__ __forceinline__ unsigned cvt_pk_bf16(float lo, float hi) { unsigned r; asm volatile("v_cvt_pk_bf16_f32 %0, %1, %2" : "=v"(r) : "v"(lo), "v"(hi)); return r; }
;     __device__ __forceinline__ void operator()(f32x4 (&acc)[2][2][4][2], const Unit& u, int wr, int wc, int fr, int fq) const {
;     ...
;                         const unsigned long long wb = wbv[m][bj][n];
;                         f32x4 eb;
;                         eb[0] = __expf(-fmaxf(__uint_as_float((unsigned)(wb & 0xffffull) << 16), -60.f)); eb[1] = __expf(-fmaxf(__uint_as_float((unsigned)((wb >> 16) & 0xffffull) << 16), -60.f));
;                         eb[2] = __expf(-fmaxf(__uint_as_float((unsigned)((wb >> 32) & 0xffffull) << 16), -60.f)); eb[3] = __expf(-fmaxf(__uint_as_float((unsigned)((wb >> 48) & 0xffffull) << 16), -60.f));
;                         if (u.kh == 0) {
;                             const unsigned long long wa = wav[m][bj][n];
;                             f32x4 ea;
;                             ea[0] = __expf(-__uint_as_float((unsigned)(wa & 0xffffull) << 16)); ea[1] = __expf(-__uint_as_float((unsigned)((wa >> 16) & 0xffffull) << 16));
;                             ea[2] = __expf(-__uint_as_float((unsigned)((wa >> 32) & 0xffffull) << 16)); ea[3] = __expf(-__uint_as_float((unsigned)((wa >> 48) & 0xffffull) << 16));
; #pragma unroll
;                             for (int e_ = 0; e_ < 4; ++e_) acc[ai][bj][m][n][e_] *= (1.0f + eb[e_]) * __builtin_amdgcn_rcpf(1.0f + ea[e_]);
;                         } else {
;                             f32x4 o;
; #pragma unroll
;                             for (int e_ = 0; e_ < 4; ++e_) o[e_] = acc[ai][bj][m][n][e_] * __builtin_amdgcn_rcpf(1.0f + eb[e_]);
;                             *(unsigned long long*)(merged + off + bj * HALF + 16 * n) = (unsigned long long)cvt_pk_bf16(o[0], o[1]) | ((unsigned long long)cvt_pk_bf16(o[2], o[3]) << 32);
.LBB0_1023:
	s_waitcnt vmcnt(12)
	v_lshlrev_b32_e32 v1, 16, v200
	v_max_f32_e32 v1, v1, v1
	v_max_f32_e32 v1, 0xc2700000, v1
	v_mul_f32_e32 v1, 0xbfb8aa3b, v1
	v_exp_f32_e32 v202, v1
	v_and_b32_e32 v1, 0xffff0000, v200
	v_max_f32_e32 v1, v1, v1
	v_max_f32_e32 v1, 0xc2700000, v1
	v_mul_f32_e32 v1, 0xbfb8aa3b, v1
	v_exp_f32_e32 v203, v1
	v_alignbit_b32 v1, v201, v200, 16
	v_and_b32_e32 v1, 0xffff0000, v1
	v_max_f32_e32 v1, v1, v1
	v_max_f32_e32 v1, 0xc2700000, v1
	v_mul_f32_e32 v1, 0xbfb8aa3b, v1
	v_exp_f32_e32 v200, v1
	v_and_b32_e32 v1, 0xffff0000, v201
	v_max_f32_e32 v1, v1, v1
	v_max_f32_e32 v1, 0xc2700000, v1
	v_mul_f32_e32 v1, 0xbfb8aa3b, v1
	v_exp_f32_e32 v201, v1
	s_and_b64 vcc, exec, s[4:5]
	s_mov_b64 s[6:7], -1
	s_cbranch_vccnz .LBB0_1025
	v_add_f32_e32 v204, 1.0, v203
	v_add_f32_e32 v205, 1.0, v200
	v_add_f32_e32 v1, 1.0, v202
	v_rcp_f32_e32 v204, v204
	v_rcp_f32_e32 v205, v205
	v_add_f32_e32 v206, 1.0, v201
	v_rcp_f32_e32 v1, v1
	v_rcp_f32_e32 v206, v206
	v_mul_f32_e32 v204, v29, v204
	v_mul_f32_e32 v205, v30, v205
	s_mov_b64 s[6:7], 0
	v_mul_f32_e32 v1, v28, v1
	v_mul_f32_e32 v206, v31, v206
	v_cvt_pk_bf16_f32 v204, v1, v204
	v_cvt_pk_bf16_f32 v205, v205, v206
	v_mov_b32_e32 v242, v204
	v_mov_b32_e32 v243, v205
	v_lshl_add_u64 v[246:247], v[208:209], 0, v[244:245]
	s_nop 0
	v_permlane32_swap_b32_e32 v240, v242
	v_permlane32_swap_b32_e32 v241, v243
	s_nop 0
	v_permlane16_swap_b32_e32 v240, v242
	v_permlane16_swap_b32_e32 v241, v243
	s_nop 1
	global_store_dwordx4 v[246:247], v[240:243], off offset:256

; __device__ __forceinline__ unsigned cvt_pk_bf16(float lo, float hi) { unsigned r; asm volatile("v_cvt_pk_bf16_f32 %0, %1, %2" : "=v"(r) : "v"(lo), "v"(hi)); return r; }
;     __device__ __forceinline__ void operator()(f32x4 (&acc)[2][2][4][2], const Unit& u, int wr, int wc, int fr, int fq) const {
;     ...
;                         const unsigned long long wb = wbv[m][bj][n];
;                         f32x4 eb;
;                         eb[0] = __expf(-fmaxf(__uint_as_float((unsigned)(wb & 0xffffull) << 16), -60.f)); eb[1] = __expf(-fmaxf(__uint_as_float((unsigned)((wb >> 16) & 0xffffull) << 16), -60.f));
;                         eb[2] = __expf(-fmaxf(__uint_as_float((unsigned)((wb >> 32) & 0xffffull) << 16), -60.f)); eb[3] = __expf(-fmaxf(__uint_as_float((unsigned)((wb >> 48) & 0xffffull) << 16), -60.f));
;                         if (u.kh == 0) {
;                             const unsigned long long wa = wav[m][bj][n];
;                             f32x4 ea;
;                             ea[0] = __expf(-__uint_as_float((unsigned)(wa & 0xffffull) << 16)); ea[1] = __expf(-__uint_as_float((unsigned)((wa >> 16) & 0xffffull) << 16));
;                             ea[2] = __expf(-__uint_as_float((unsigned)((wa >> 32) & 0xffffull) << 16)); ea[3] = __expf(-__uint_as_float((unsigned)((wa >> 48) & 0xffffull) << 16));
; #pragma unroll
;                             for (int e_ = 0; e_ < 4; ++e_) acc[ai][bj][m][n][e_] *= (1.0f + eb[e_]) * __builtin_amdgcn_rcpf(1.0f + ea[e_]);
;                         } else {
;                             f32x4 o;
; #pragma unroll
;                             for (int e_ = 0; e_ < 4; ++e_) o[e_] = acc[ai][bj][m][n][e_] * __builtin_amdgcn_rcpf(1.0f + eb[e_]);
;                             *(unsigned long long*)(merged + off + bj * HALF + 16 * n) = (unsigned long long)cvt_pk_bf16(o[0], o[1]) | ((unsigned long long)cvt_pk_bf16(o[2], o[3]) << 32);
.LBB0_1027:
	s_waitcnt vmcnt(11)
	v_lshlrev_b32_e32 v1, 16, v194
	v_max_f32_e32 v1, v1, v1
	v_max_f32_e32 v1, 0xc2700000, v1
	v_mul_f32_e32 v1, 0xbfb8aa3b, v1
	v_lshlrev_b64 v[200:201], 11, v[196:197]
	v_exp_f32_e32 v196, v1
	v_and_b32_e32 v1, 0xffff0000, v194
	v_max_f32_e32 v1, v1, v1
	v_max_f32_e32 v1, 0xc2700000, v1
	v_mul_f32_e32 v1, 0xbfb8aa3b, v1
	v_exp_f32_e32 v197, v1
	v_alignbit_b32 v1, v195, v194, 16
	v_and_b32_e32 v1, 0xffff0000, v1
	v_max_f32_e32 v1, v1, v1
	v_max_f32_e32 v1, 0xc2700000, v1
	v_mul_f32_e32 v1, 0xbfb8aa3b, v1
	v_exp_f32_e32 v198, v1
	v_and_b32_e32 v1, 0xffff0000, v195
	v_max_f32_e32 v1, v1, v1
	v_max_f32_e32 v1, 0xc2700000, v1
	v_mul_f32_e32 v1, 0xbfb8aa3b, v1
	v_exp_f32_e32 v199, v1
	v_lshl_add_u64 v[194:195], s[14:15], 0, v[200:201]
	s_mov_b64 s[6:7], -1
	s_and_b64 vcc, exec, s[4:5]
	v_lshl_add_u64 v[194:195], v[2:3], 1, v[194:195]
	s_cbranch_vccnz .LBB0_1029
	v_add_f32_e32 v200, 1.0, v197
	v_add_f32_e32 v201, 1.0, v198
	v_add_f32_e32 v1, 1.0, v196
	v_rcp_f32_e32 v200, v200
	v_rcp_f32_e32 v201, v201
	v_add_f32_e32 v202, 1.0, v199
	v_rcp_f32_e32 v1, v1
	v_rcp_f32_e32 v202, v202
	v_mul_f32_e32 v200, v57, v200
	v_mul_f32_e32 v201, v58, v201
	s_mov_b64 s[6:7], 0
	v_mul_f32_e32 v1, v56, v1
	v_mul_f32_e32 v202, v59, v202
	v_cvt_pk_bf16_f32 v200, v1, v200
	v_cvt_pk_bf16_f32 v201, v201, v202
	v_and_b32_e32 v244, 48, v254
	v_mov_b32_e32 v245, 0
	v_lshrrev_b32_e32 v244, 1, v244
	v_mov_b32_e32 v240, v200
	v_mov_b32_e32 v241, v201

; __device__ __forceinline__ unsigned cvt_pk_bf16(float lo, float hi) { unsigned r; asm volatile("v_cvt_pk_bf16_f32 %0, %1, %2" : "=v"(r) : "v"(lo), "v"(hi)); return r; }
;     __device__ __forceinline__ void operator()(f32x4 (&acc)[2][2][4][2], const Unit& u, int wr, int wc, int fr, int fq) const {
;     ...
;                         const unsigned long long wb = wbv[m][bj][n];
;                         f32x4 eb;
;                         eb[0] = __expf(-fmaxf(__uint_as_float((unsigned)(wb & 0xffffull) << 16), -60.f)); eb[1] = __expf(-fmaxf(__uint_as_float((unsigned)((wb >> 16) & 0xffffull) << 16), -60.f));
;                         eb[2] = __expf(-fmaxf(__uint_as_float((unsigned)((wb >> 32) & 0xffffull) << 16), -60.f)); eb[3] = __expf(-fmaxf(__uint_as_float((unsigned)((wb >> 48) & 0xffffull) << 16), -60.f));
;                         if (u.kh == 0) {
;                             const unsigned long long wa = wav[m][bj][n];
;                             f32x4 ea;
;                             ea[0] = __expf(-__uint_as_float((unsigned)(wa & 0xffffull) << 16)); ea[1] = __expf(-__uint_as_float((unsigned)((wa >> 16) & 0xffffull) << 16));
;                             ea[2] = __expf(-__uint_as_float((unsigned)((wa >> 32) & 0xffffull) << 16)); ea[3] = __expf(-__uint_as_float((unsigned)((wa >> 48) & 0xffffull) << 16));
; #pragma unroll
;                             for (int e_ = 0; e_ < 4; ++e_) acc[ai][bj][m][n][e_] *= (1.0f + eb[e_]) * __builtin_amdgcn_rcpf(1.0f + ea[e_]);
;                         } else {
;                             f32x4 o;
; #pragma unroll
;                             for (int e_ = 0; e_ < 4; ++e_) o[e_] = acc[ai][bj][m][n][e_] * __builtin_amdgcn_rcpf(1.0f + eb[e_]);
;                             *(unsigned long long*)(merged + off + bj * HALF + 16 * n) = (unsigned long long)cvt_pk_bf16(o[0], o[1]) | ((unsigned long long)cvt_pk_bf16(o[2], o[3]) << 32);
.LBB0_1031:
	s_waitcnt vmcnt(10)
	v_lshlrev_b32_e32 v1, 16, v190
	v_max_f32_e32 v1, v1, v1
	v_max_f32_e32 v1, 0xc2700000, v1
	v_mul_f32_e32 v1, 0xbfb8aa3b, v1
	v_exp_f32_e32 v192, v1
	v_and_b32_e32 v1, 0xffff0000, v190
	v_max_f32_e32 v1, v1, v1
	v_max_f32_e32 v1, 0xc2700000, v1
	v_mul_f32_e32 v1, 0xbfb8aa3b, v1
	v_exp_f32_e32 v193, v1
	v_alignbit_b32 v1, v191, v190, 16
	v_and_b32_e32 v1, 0xffff0000, v1
	v_max_f32_e32 v1, v1, v1
	v_max_f32_e32 v1, 0xc2700000, v1
	v_mul_f32_e32 v1, 0xbfb8aa3b, v1
	v_exp_f32_e32 v190, v1
	v_and_b32_e32 v1, 0xffff0000, v191
	v_max_f32_e32 v1, v1, v1
	v_max_f32_e32 v1, 0xc2700000, v1
	v_mul_f32_e32 v1, 0xbfb8aa3b, v1
	v_exp_f32_e32 v191, v1
	s_and_b64 vcc, exec, s[4:5]
	s_mov_b64 s[6:7], -1
	s_cbranch_vccnz .LBB0_1033
	v_add_f32_e32 v196, 1.0, v193
	v_add_f32_e32 v197, 1.0, v190
	v_add_f32_e32 v1, 1.0, v192
	v_rcp_f32_e32 v196, v196
	v_rcp_f32_e32 v197, v197
	v_add_f32_e32 v198, 1.0, v191
	v_rcp_f32_e32 v1, v1
	v_rcp_f32_e32 v198, v198
	v_mul_f32_e32 v196, v53, v196
	v_mul_f32_e32 v197, v54, v197
	s_mov_b64 s[6:7], 0
	v_mul_f32_e32 v1, v52, v1
	v_mul_f32_e32 v198, v55, v198
	v_cvt_pk_bf16_f32 v196, v1, v196
	v_cvt_pk_bf16_f32 v197, v197, v198
	v_mov_b32_e32 v242, v196
	v_mov_b32_e32 v243, v197
	v_lshl_add_u64 v[246:247], v[194:195], 0, v[244:245]
	s_nop 0
	v_permlane32_swap_b32_e32 v240, v242
	v_permlane32_swap_b32_e32 v241, v243
	s_nop 0
	v_permlane16_swap_b32_e32 v240, v242
	v_permlane16_swap_b32_e32 v241, v243
	s_nop 1
	global_store_dwordx4 v[246:247], v[240:243], off

; __device__ __forceinline__ unsigned cvt_pk_bf16(float lo, float hi) { unsigned r; asm volatile("v_cvt_pk_bf16_f32 %0, %1, %2" : "=v"(r) : "v"(lo), "v"(hi)); return r; }
;     __device__ __forceinline__ void operator()(f32x4 (&acc)[2][2][4][2], const Unit& u, int wr, int wc, int fr, int fq) const {
;     ...
;                         const unsigned long long wb = wbv[m][bj][n];
;                         f32x4 eb;
;                         eb[0] = __expf(-fmaxf(__uint_as_float((unsigned)(wb & 0xffffull) << 16), -60.f)); eb[1] = __expf(-fmaxf(__uint_as_float((unsigned)((wb >> 16) & 0xffffull) << 16), -60.f));
;                         eb[2] = __expf(-fmaxf(__uint_as_float((unsigned)((wb >> 32) & 0xffffull) << 16), -60.f)); eb[3] = __expf(-fmaxf(__uint_as_float((unsigned)((wb >> 48) & 0xffffull) << 16), -60.f));
;                         if (u.kh == 0) {
;                             const unsigned long long wa = wav[m][bj][n];
;                             f32x4 ea;
;                             ea[0] = __expf(-__uint_as_float((unsigned)(wa & 0xffffull) << 16)); ea[1] = __expf(-__uint_as_float((unsigned)((wa >> 16) & 0xffffull) << 16));
;                             ea[2] = __expf(-__uint_as_float((unsigned)((wa >> 32) & 0xffffull) << 16)); ea[3] = __expf(-__uint_as_float((unsigned)((wa >> 48) & 0xffffull) << 16));
; #pragma unroll
;                             for (int e_ = 0; e_ < 4; ++e_) acc[ai][bj][m][n][e_] *= (1.0f + eb[e_]) * __builtin_amdgcn_rcpf(1.0f + ea[e_]);
;                         } else {
;                             f32x4 o;
; #pragma unroll
;                             for (int e_ = 0; e_ < 4; ++e_) o[e_] = acc[ai][bj][m][n][e_] * __builtin_amdgcn_rcpf(1.0f + eb[e_]);
;                             *(unsigned long long*)(merged + off + bj * HALF + 16 * n) = (unsigned long long)cvt_pk_bf16(o[0], o[1]) | ((unsigned long long)cvt_pk_bf16(o[2], o[3]) << 32);
.LBB0_1035:
	s_waitcnt vmcnt(9)
	v_lshlrev_b32_e32 v1, 16, v186
	v_max_f32_e32 v1, v1, v1
	v_max_f32_e32 v1, 0xc2700000, v1
	v_mul_f32_e32 v1, 0xbfb8aa3b, v1
	v_exp_f32_e32 v188, v1
	v_and_b32_e32 v1, 0xffff0000, v186
	v_max_f32_e32 v1, v1, v1
	v_max_f32_e32 v1, 0xc2700000, v1
	v_mul_f32_e32 v1, 0xbfb8aa3b, v1
	v_exp_f32_e32 v189, v1
	v_alignbit_b32 v1, v187, v186, 16
	v_and_b32_e32 v1, 0xffff0000, v1
	v_max_f32_e32 v1, v1, v1
	v_max_f32_e32 v1, 0xc2700000, v1
	v_mul_f32_e32 v1, 0xbfb8aa3b, v1
	v_exp_f32_e32 v186, v1
	v_and_b32_e32 v1, 0xffff0000, v187
	v_max_f32_e32 v1, v1, v1
	v_max_f32_e32 v1, 0xc2700000, v1
	v_mul_f32_e32 v1, 0xbfb8aa3b, v1
	v_exp_f32_e32 v187, v1
	s_and_b64 vcc, exec, s[4:5]
	s_mov_b64 s[6:7], -1
	s_cbranch_vccnz .LBB0_1037
	v_add_f32_e32 v190, 1.0, v189
	v_add_f32_e32 v191, 1.0, v186
	v_add_f32_e32 v1, 1.0, v188
	v_rcp_f32_e32 v190, v190
	v_rcp_f32_e32 v191, v191
	v_add_f32_e32 v192, 1.0, v187
	v_rcp_f32_e32 v1, v1
	v_rcp_f32_e32 v192, v192
	v_mul_f32_e32 v190, v25, v190
	v_mul_f32_e32 v191, v26, v191
	s_mov_b64 s[6:7], 0
	v_mul_f32_e32 v1, v24, v1
	v_mul_f32_e32 v192, v27, v192
	v_cvt_pk_bf16_f32 v190, v1, v190
	v_cvt_pk_bf16_f32 v191, v191, v192
	v_mov_b32_e32 v240, v190
	v_mov_b32_e32 v241, v191

; __device__ __forceinline__ unsigned cvt_pk_bf16(float lo, float hi) { unsigned r; asm volatile("v_cvt_pk_bf16_f32 %0, %1, %2" : "=v"(r) : "v"(lo), "v"(hi)); return r; }
;     __device__ __forceinline__ void operator()(f32x4 (&acc)[2][2][4][2], const Unit& u, int wr, int wc, int fr, int fq) const {
;     ...
;                         const unsigned long long wb = wbv[m][bj][n];
;                         f32x4 eb;
;                         eb[0] = __expf(-fmaxf(__uint_as_float((unsigned)(wb & 0xffffull) << 16), -60.f)); eb[1] = __expf(-fmaxf(__uint_as_float((unsigned)((wb >> 16) & 0xffffull) << 16), -60.f));
;                         eb[2] = __expf(-fmaxf(__uint_as_float((unsigned)((wb >> 32) & 0xffffull) << 16), -60.f)); eb[3] = __expf(-fmaxf(__uint_as_float((unsigned)((wb >> 48) & 0xffffull) << 16), -60.f));
;                         if (u.kh == 0) {
;                             const unsigned long long wa = wav[m][bj][n];
;                             f32x4 ea;
;                             ea[0] = __expf(-__uint_as_float((unsigned)(wa & 0xffffull) << 16)); ea[1] = __expf(-__uint_as_float((unsigned)((wa >> 16) & 0xffffull) << 16));
;                             ea[2] = __expf(-__uint_as_float((unsigned)((wa >> 32) & 0xffffull) << 16)); ea[3] = __expf(-__uint_as_float((unsigned)((wa >> 48) & 0xffffull) << 16));
; #pragma unroll
;                             for (int e_ = 0; e_ < 4; ++e_) acc[ai][bj][m][n][e_] *= (1.0f + eb[e_]) * __builtin_amdgcn_rcpf(1.0f + ea[e_]);
;                         } else {
;                             f32x4 o;
; #pragma unroll
;                             for (int e_ = 0; e_ < 4; ++e_) o[e_] = acc[ai][bj][m][n][e_] * __builtin_amdgcn_rcpf(1.0f + eb[e_]);
;                             *(unsigned long long*)(merged + off + bj * HALF + 16 * n) = (unsigned long long)cvt_pk_bf16(o[0], o[1]) | ((unsigned long long)cvt_pk_bf16(o[2], o[3]) << 32);
.LBB0_1039:
	s_waitcnt vmcnt(8)
	v_lshlrev_b32_e32 v1, 16, v182
	v_max_f32_e32 v1, v1, v1
	v_max_f32_e32 v1, 0xc2700000, v1
	v_mul_f32_e32 v1, 0xbfb8aa3b, v1
	v_exp_f32_e32 v184, v1
	v_and_b32_e32 v1, 0xffff0000, v182
	v_max_f32_e32 v1, v1, v1
	v_max_f32_e32 v1, 0xc2700000, v1
	v_mul_f32_e32 v1, 0xbfb8aa3b, v1
	v_exp_f32_e32 v185, v1
	v_alignbit_b32 v1, v183, v182, 16
	v_and_b32_e32 v1, 0xffff0000, v1
	v_max_f32_e32 v1, v1, v1
	v_max_f32_e32 v1, 0xc2700000, v1
	v_mul_f32_e32 v1, 0xbfb8aa3b, v1
	v_exp_f32_e32 v182, v1
	v_and_b32_e32 v1, 0xffff0000, v183
	v_max_f32_e32 v1, v1, v1
	v_max_f32_e32 v1, 0xc2700000, v1
	v_mul_f32_e32 v1, 0xbfb8aa3b, v1
	v_exp_f32_e32 v183, v1
	s_and_b64 vcc, exec, s[4:5]
	s_mov_b64 s[6:7], -1
	s_cbranch_vccnz .LBB0_1041
	v_add_f32_e32 v186, 1.0, v185
	v_add_f32_e32 v187, 1.0, v182
	v_add_f32_e32 v1, 1.0, v184
	v_rcp_f32_e32 v186, v186
	v_rcp_f32_e32 v187, v187
	v_add_f32_e32 v188, 1.0, v183
	v_rcp_f32_e32 v1, v1
	v_rcp_f32_e32 v188, v188
	v_mul_f32_e32 v186, v21, v186
	v_mul_f32_e32 v187, v22, v187
	s_mov_b64 s[6:7], 0
	v_mul_f32_e32 v1, v20, v1
	v_mul_f32_e32 v188, v23, v188
	v_cvt_pk_bf16_f32 v186, v1, v186
	v_cvt_pk_bf16_f32 v187, v187, v188
	v_mov_b32_e32 v242, v186
	v_mov_b32_e32 v243, v187
	v_lshl_add_u64 v[246:247], v[194:195], 0, v[244:245]
	s_nop 0
	v_permlane32_swap_b32_e32 v240, v242
	v_permlane32_swap_b32_e32 v241, v243
	s_nop 0
	v_permlane16_swap_b32_e32 v240, v242
	v_permlane16_swap_b32_e32 v241, v243
	s_nop 1
	global_store_dwordx4 v[246:247], v[240:243], off offset:256

; __device__ __forceinline__ unsigned cvt_pk_bf16(float lo, float hi) { unsigned r; asm volatile("v_cvt_pk_bf16_f32 %0, %1, %2" : "=v"(r) : "v"(lo), "v"(hi)); return r; }
;     __device__ __forceinline__ void operator()(f32x4 (&acc)[2][2][4][2], const Unit& u, int wr, int wc, int fr, int fq) const {
;     ...
;                         const unsigned long long wb = wbv[m][bj][n];
;                         f32x4 eb;
;                         eb[0] = __expf(-fmaxf(__uint_as_float((unsigned)(wb & 0xffffull) << 16), -60.f)); eb[1] = __expf(-fmaxf(__uint_as_float((unsigned)((wb >> 16) & 0xffffull) << 16), -60.f));
;                         eb[2] = __expf(-fmaxf(__uint_as_float((unsigned)((wb >> 32) & 0xffffull) << 16), -60.f)); eb[3] = __expf(-fmaxf(__uint_as_float((unsigned)((wb >> 48) & 0xffffull) << 16), -60.f));
;                         if (u.kh == 0) {
;                             const unsigned long long wa = wav[m][bj][n];
;                             f32x4 ea;
;                             ea[0] = __expf(-__uint_as_float((unsigned)(wa & 0xffffull) << 16)); ea[1] = __expf(-__uint_as_float((unsigned)((wa >> 16) & 0xffffull) << 16));
;                             ea[2] = __expf(-__uint_as_float((unsigned)((wa >> 32) & 0xffffull) << 16)); ea[3] = __expf(-__uint_as_float((unsigned)((wa >> 48) & 0xffffull) << 16));
; #pragma unroll
;                             for (int e_ = 0; e_ < 4; ++e_) acc[ai][bj][m][n][e_] *= (1.0f + eb[e_]) * __builtin_amdgcn_rcpf(1.0f + ea[e_]);
;                         } else {
;                             f32x4 o;
; #pragma unroll
;                             for (int e_ = 0; e_ < 4; ++e_) o[e_] = acc[ai][bj][m][n][e_] * __builtin_amdgcn_rcpf(1.0f + eb[e_]);
;                             *(unsigned long long*)(merged + off + bj * HALF + 16 * n) = (unsigned long long)cvt_pk_bf16(o[0], o[1]) | ((unsigned long long)cvt_pk_bf16(o[2], o[3]) << 32);
.LBB0_1043:
	s_waitcnt vmcnt(7)
	v_lshlrev_b32_e32 v1, 16, v176
	v_max_f32_e32 v1, v1, v1
	v_max_f32_e32 v1, 0xc2700000, v1
	v_mul_f32_e32 v1, 0xbfb8aa3b, v1
	v_lshlrev_b64 v[182:183], 11, v[178:179]
	v_exp_f32_e32 v178, v1
	v_and_b32_e32 v1, 0xffff0000, v176
	v_max_f32_e32 v1, v1, v1
	v_max_f32_e32 v1, 0xc2700000, v1
	v_mul_f32_e32 v1, 0xbfb8aa3b, v1
	v_exp_f32_e32 v179, v1
	v_alignbit_b32 v1, v177, v176, 16
	v_and_b32_e32 v1, 0xffff0000, v1
	v_max_f32_e32 v1, v1, v1
	v_max_f32_e32 v1, 0xc2700000, v1
	v_mul_f32_e32 v1, 0xbfb8aa3b, v1
	v_exp_f32_e32 v180, v1
	v_and_b32_e32 v1, 0xffff0000, v177
	v_max_f32_e32 v1, v1, v1
	v_max_f32_e32 v1, 0xc2700000, v1
	v_mul_f32_e32 v1, 0xbfb8aa3b, v1
	v_exp_f32_e32 v181, v1
	v_lshl_add_u64 v[176:177], s[14:15], 0, v[182:183]
	s_mov_b64 s[6:7], -1
	s_and_b64 vcc, exec, s[4:5]
	v_lshl_add_u64 v[176:177], v[2:3], 1, v[176:177]
	s_cbranch_vccnz .LBB0_1045
	v_add_f32_e32 v182, 1.0, v179
	v_add_f32_e32 v183, 1.0, v180
	v_add_f32_e32 v1, 1.0, v178
	v_rcp_f32_e32 v182, v182
	v_rcp_f32_e32 v183, v183
	v_add_f32_e32 v184, 1.0, v181
	v_rcp_f32_e32 v1, v1
	v_rcp_f32_e32 v184, v184
	v_mul_f32_e32 v182, v49, v182
	v_mul_f32_e32 v183, v50, v183
	s_mov_b64 s[6:7], 0
	v_mul_f32_e32 v1, v48, v1
	v_mul_f32_e32 v184, v51, v184
	v_cvt_pk_bf16_f32 v182, v1, v182
	v_cvt_pk_bf16_f32 v183, v183, v184
	v_and_b32_e32 v244, 48, v254
	v_mov_b32_e32 v245, 0
	v_lshrrev_b32_e32 v244, 1, v244
	v_mov_b32_e32 v240, v182
	v_mov_b32_e32 v241, v183

; __device__ __forceinline__ unsigned cvt_pk_bf16(float lo, float hi) { unsigned r; asm volatile("v_cvt_pk_bf16_f32 %0, %1, %2" : "=v"(r) : "v"(lo), "v"(hi)); return r; }
;     __device__ __forceinline__ void operator()(f32x4 (&acc)[2][2][4][2], const Unit& u, int wr, int wc, int fr, int fq) const {
;     ...
;                         const unsigned long long wb = wbv[m][bj][n];
;                         f32x4 eb;
;                         eb[0] = __expf(-fmaxf(__uint_as_float((unsigned)(wb & 0xffffull) << 16), -60.f)); eb[1] = __expf(-fmaxf(__uint_as_float((unsigned)((wb >> 16) & 0xffffull) << 16), -60.f));
;                         eb[2] = __expf(-fmaxf(__uint_as_float((unsigned)((wb >> 32) & 0xffffull) << 16), -60.f)); eb[3] = __expf(-fmaxf(__uint_as_float((unsigned)((wb >> 48) & 0xffffull) << 16), -60.f));
;                         if (u.kh == 0) {
;                             const unsigned long long wa = wav[m][bj][n];
;                             f32x4 ea;
;                             ea[0] = __expf(-__uint_as_float((unsigned)(wa & 0xffffull) << 16)); ea[1] = __expf(-__uint_as_float((unsigned)((wa >> 16) & 0xffffull) << 16));
;                             ea[2] = __expf(-__uint_as_float((unsigned)((wa >> 32) & 0xffffull) << 16)); ea[3] = __expf(-__uint_as_float((unsigned)((wa >> 48) & 0xffffull) << 16));
; #pragma unroll
;                             for (int e_ = 0; e_ < 4; ++e_) acc[ai][bj][m][n][e_] *= (1.0f + eb[e_]) * __builtin_amdgcn_rcpf(1.0f + ea[e_]);
;                         } else {
;                             f32x4 o;
; #pragma unroll
;                             for (int e_ = 0; e_ < 4; ++e_) o[e_] = acc[ai][bj][m][n][e_] * __builtin_amdgcn_rcpf(1.0f + eb[e_]);
;                             *(unsigned long long*)(merged + off + bj * HALF + 16 * n) = (unsigned long long)cvt_pk_bf16(o[0], o[1]) | ((unsigned long long)cvt_pk_bf16(o[2], o[3]) << 32);
.LBB0_1047:
	s_waitcnt vmcnt(6)
	v_lshlrev_b32_e32 v1, 16, v172
	v_max_f32_e32 v1, v1, v1
	v_max_f32_e32 v1, 0xc2700000, v1
	v_mul_f32_e32 v1, 0xbfb8aa3b, v1
	v_exp_f32_e32 v174, v1
	v_and_b32_e32 v1, 0xffff0000, v172
	v_max_f32_e32 v1, v1, v1
	v_max_f32_e32 v1, 0xc2700000, v1
	v_mul_f32_e32 v1, 0xbfb8aa3b, v1
	v_exp_f32_e32 v175, v1
	v_alignbit_b32 v1, v173, v172, 16
	v_and_b32_e32 v1, 0xffff0000, v1
	v_max_f32_e32 v1, v1, v1
	v_max_f32_e32 v1, 0xc2700000, v1
	v_mul_f32_e32 v1, 0xbfb8aa3b, v1
	v_exp_f32_e32 v172, v1
	v_and_b32_e32 v1, 0xffff0000, v173
	v_max_f32_e32 v1, v1, v1
	v_max_f32_e32 v1, 0xc2700000, v1
	v_mul_f32_e32 v1, 0xbfb8aa3b, v1
	v_exp_f32_e32 v173, v1
	s_and_b64 vcc, exec, s[4:5]
	s_mov_b64 s[6:7], -1
	s_cbranch_vccnz .LBB0_1049
	v_add_f32_e32 v178, 1.0, v175
	v_add_f32_e32 v179, 1.0, v172
	v_add_f32_e32 v1, 1.0, v174
	v_rcp_f32_e32 v178, v178
	v_rcp_f32_e32 v179, v179
	v_add_f32_e32 v180, 1.0, v173
	v_rcp_f32_e32 v1, v1
	v_rcp_f32_e32 v180, v180
	v_mul_f32_e32 v178, v45, v178
	v_mul_f32_e32 v179, v46, v179
	s_mov_b64 s[6:7], 0
	v_mul_f32_e32 v1, v44, v1
	v_mul_f32_e32 v180, v47, v180
	v_cvt_pk_bf16_f32 v178, v1, v178
	v_cvt_pk_bf16_f32 v179, v179, v180
	v_mov_b32_e32 v242, v178
	v_mov_b32_e32 v243, v179
	v_lshl_add_u64 v[246:247], v[176:177], 0, v[244:245]
	s_nop 0
	v_permlane32_swap_b32_e32 v240, v242
	v_permlane32_swap_b32_e32 v241, v243
	s_nop 0
	v_permlane16_swap_b32_e32 v240, v242
	v_permlane16_swap_b32_e32 v241, v243
	s_nop 1
	global_store_dwordx4 v[246:247], v[240:243], off

; __device__ __forceinline__ unsigned cvt_pk_bf16(float lo, float hi) { unsigned r; asm volatile("v_cvt_pk_bf16_f32 %0, %1, %2" : "=v"(r) : "v"(lo), "v"(hi)); return r; }
;     __device__ __forceinline__ void operator()(f32x4 (&acc)[2][2][4][2], const Unit& u, int wr, int wc, int fr, int fq) const {
;     ...
;                         const unsigned long long wb = wbv[m][bj][n];
;                         f32x4 eb;
;                         eb[0] = __expf(-fmaxf(__uint_as_float((unsigned)(wb & 0xffffull) << 16), -60.f)); eb[1] = __expf(-fmaxf(__uint_as_float((unsigned)((wb >> 16) & 0xffffull) << 16), -60.f));
;                         eb[2] = __expf(-fmaxf(__uint_as_float((unsigned)((wb >> 32) & 0xffffull) << 16), -60.f)); eb[3] = __expf(-fmaxf(__uint_as_float((unsigned)((wb >> 48) & 0xffffull) << 16), -60.f));
;                         if (u.kh == 0) {
;                             const unsigned long long wa = wav[m][bj][n];
;                             f32x4 ea;
;                             ea[0] = __expf(-__uint_as_float((unsigned)(wa & 0xffffull) << 16)); ea[1] = __expf(-__uint_as_float((unsigned)((wa >> 16) & 0xffffull) << 16));
;                             ea[2] = __expf(-__uint_as_float((unsigned)((wa >> 32) & 0xffffull) << 16)); ea[3] = __expf(-__uint_as_float((unsigned)((wa >> 48) & 0xffffull) << 16));
; #pragma unroll
;                             for (int e_ = 0; e_ < 4; ++e_) acc[ai][bj][m][n][e_] *= (1.0f + eb[e_]) * __builtin_amdgcn_rcpf(1.0f + ea[e_]);
;                         } else {
;                             f32x4 o;
; #pragma unroll
;                             for (int e_ = 0; e_ < 4; ++e_) o[e_] = acc[ai][bj][m][n][e_] * __builtin_amdgcn_rcpf(1.0f + eb[e_]);
;                             *(unsigned long long*)(merged + off + bj * HALF + 16 * n) = (unsigned long long)cvt_pk_bf16(o[0], o[1]) | ((unsigned long long)cvt_pk_bf16(o[2], o[3]) << 32);
.LBB0_1051:
	s_waitcnt vmcnt(5)
	v_lshlrev_b32_e32 v1, 16, v168
	v_max_f32_e32 v1, v1, v1
	v_max_f32_e32 v1, 0xc2700000, v1
	v_mul_f32_e32 v1, 0xbfb8aa3b, v1
	v_exp_f32_e32 v170, v1
	v_and_b32_e32 v1, 0xffff0000, v168
	v_max_f32_e32 v1, v1, v1
	v_max_f32_e32 v1, 0xc2700000, v1
	v_mul_f32_e32 v1, 0xbfb8aa3b, v1
	v_exp_f32_e32 v171, v1
	v_alignbit_b32 v1, v169, v168, 16
	v_and_b32_e32 v1, 0xffff0000, v1
	v_max_f32_e32 v1, v1, v1
	v_max_f32_e32 v1, 0xc2700000, v1
	v_mul_f32_e32 v1, 0xbfb8aa3b, v1
	v_exp_f32_e32 v168, v1
	v_and_b32_e32 v1, 0xffff0000, v169
	v_max_f32_e32 v1, v1, v1
	v_max_f32_e32 v1, 0xc2700000, v1
	v_mul_f32_e32 v1, 0xbfb8aa3b, v1
	v_exp_f32_e32 v169, v1
	s_and_b64 vcc, exec, s[4:5]
	s_mov_b64 s[6:7], -1
	s_cbranch_vccnz .LBB0_1053
	v_add_f32_e32 v172, 1.0, v171
	v_add_f32_e32 v173, 1.0, v168
	v_add_f32_e32 v1, 1.0, v170
	v_rcp_f32_e32 v172, v172
	v_rcp_f32_e32 v173, v173
	v_add_f32_e32 v174, 1.0, v169
	v_rcp_f32_e32 v1, v1
	v_rcp_f32_e32 v174, v174
	v_mul_f32_e32 v172, v17, v172
	v_mul_f32_e32 v173, v18, v173
	s_mov_b64 s[6:7], 0
	v_mul_f32_e32 v1, v16, v1
	v_mul_f32_e32 v174, v19, v174
	v_cvt_pk_bf16_f32 v172, v1, v172
	v_cvt_pk_bf16_f32 v173, v173, v174
	v_mov_b32_e32 v240, v172
	v_mov_b32_e32 v241, v173

; __device__ __forceinline__ unsigned cvt_pk_bf16(float lo, float hi) { unsigned r; asm volatile("v_cvt_pk_bf16_f32 %0, %1, %2" : "=v"(r) : "v"(lo), "v"(hi)); return r; }
;     __device__ __forceinline__ void operator()(f32x4 (&acc)[2][2][4][2], const Unit& u, int wr, int wc, int fr, int fq) const {
;     ...
;                         const unsigned long long wb = wbv[m][bj][n];
;                         f32x4 eb;
;                         eb[0] = __expf(-fmaxf(__uint_as_float((unsigned)(wb & 0xffffull) << 16), -60.f)); eb[1] = __expf(-fmaxf(__uint_as_float((unsigned)((wb >> 16) & 0xffffull) << 16), -60.f));
;                         eb[2] = __expf(-fmaxf(__uint_as_float((unsigned)((wb >> 32) & 0xffffull) << 16), -60.f)); eb[3] = __expf(-fmaxf(__uint_as_float((unsigned)((wb >> 48) & 0xffffull) << 16), -60.f));
;                         if (u.kh == 0) {
;                             const unsigned long long wa = wav[m][bj][n];
;                             f32x4 ea;
;                             ea[0] = __expf(-__uint_as_float((unsigned)(wa & 0xffffull) << 16)); ea[1] = __expf(-__uint_as_float((unsigned)((wa >> 16) & 0xffffull) << 16));
;                             ea[2] = __expf(-__uint_as_float((unsigned)((wa >> 32) & 0xffffull) << 16)); ea[3] = __expf(-__uint_as_float((unsigned)((wa >> 48) & 0xffffull) << 16));
; #pragma unroll
;                             for (int e_ = 0; e_ < 4; ++e_) acc[ai][bj][m][n][e_] *= (1.0f + eb[e_]) * __builtin_amdgcn_rcpf(1.0f + ea[e_]);
;                         } else {
;                             f32x4 o;
; #pragma unroll
;                             for (int e_ = 0; e_ < 4; ++e_) o[e_] = acc[ai][bj][m][n][e_] * __builtin_amdgcn_rcpf(1.0f + eb[e_]);
;                             *(unsigned long long*)(merged + off + bj * HALF + 16 * n) = (unsigned long long)cvt_pk_bf16(o[0], o[1]) | ((unsigned long long)cvt_pk_bf16(o[2], o[3]) << 32);
.LBB0_1055:
	s_waitcnt vmcnt(4)
	v_lshlrev_b32_e32 v1, 16, v164
	v_max_f32_e32 v1, v1, v1
	v_max_f32_e32 v1, 0xc2700000, v1
	v_mul_f32_e32 v1, 0xbfb8aa3b, v1
	v_exp_f32_e32 v166, v1
	v_and_b32_e32 v1, 0xffff0000, v164
	v_max_f32_e32 v1, v1, v1
	v_max_f32_e32 v1, 0xc2700000, v1
	v_mul_f32_e32 v1, 0xbfb8aa3b, v1
	v_exp_f32_e32 v167, v1
	v_alignbit_b32 v1, v165, v164, 16
	v_and_b32_e32 v1, 0xffff0000, v1
	v_max_f32_e32 v1, v1, v1
	v_max_f32_e32 v1, 0xc2700000, v1
	v_mul_f32_e32 v1, 0xbfb8aa3b, v1
	v_exp_f32_e32 v164, v1
	v_and_b32_e32 v1, 0xffff0000, v165
	v_max_f32_e32 v1, v1, v1
	v_max_f32_e32 v1, 0xc2700000, v1
	v_mul_f32_e32 v1, 0xbfb8aa3b, v1
	v_exp_f32_e32 v165, v1
	s_and_b64 vcc, exec, s[4:5]
	s_mov_b64 s[6:7], -1
	s_cbranch_vccnz .LBB0_1057
	v_add_f32_e32 v168, 1.0, v167
	v_add_f32_e32 v169, 1.0, v164
	v_add_f32_e32 v1, 1.0, v166
	v_rcp_f32_e32 v168, v168
	v_rcp_f32_e32 v169, v169
	v_add_f32_e32 v170, 1.0, v165
	v_rcp_f32_e32 v1, v1
	v_rcp_f32_e32 v170, v170
	v_mul_f32_e32 v168, v13, v168
	v_mul_f32_e32 v169, v14, v169
	s_mov_b64 s[6:7], 0
	v_mul_f32_e32 v1, v12, v1
	v_mul_f32_e32 v170, v15, v170
	v_cvt_pk_bf16_f32 v168, v1, v168
	v_cvt_pk_bf16_f32 v169, v169, v170
	v_mov_b32_e32 v242, v168
	v_mov_b32_e32 v243, v169
	v_lshl_add_u64 v[246:247], v[176:177], 0, v[244:245]
	s_nop 0
	v_permlane32_swap_b32_e32 v240, v242
	v_permlane32_swap_b32_e32 v241, v243
	s_nop 0
	v_permlane16_swap_b32_e32 v240, v242
	v_permlane16_swap_b32_e32 v241, v243
	s_nop 1
	global_store_dwordx4 v[246:247], v[240:243], off offset:256

; __device__ __forceinline__ unsigned cvt_pk_bf16(float lo, float hi) { unsigned r; asm volatile("v_cvt_pk_bf16_f32 %0, %1, %2" : "=v"(r) : "v"(lo), "v"(hi)); return r; }
;     __device__ __forceinline__ void operator()(f32x4 (&acc)[2][2][4][2], const Unit& u, int wr, int wc, int fr, int fq) const {
;     ...
;                         const unsigned long long wb = wbv[m][bj][n];
;                         f32x4 eb;
;                         eb[0] = __expf(-fmaxf(__uint_as_float((unsigned)(wb & 0xffffull) << 16), -60.f)); eb[1] = __expf(-fmaxf(__uint_as_float((unsigned)((wb >> 16) & 0xffffull) << 16), -60.f));
;                         eb[2] = __expf(-fmaxf(__uint_as_float((unsigned)((wb >> 32) & 0xffffull) << 16), -60.f)); eb[3] = __expf(-fmaxf(__uint_as_float((unsigned)((wb >> 48) & 0xffffull) << 16), -60.f));
;                         if (u.kh == 0) {
;                             const unsigned long long wa = wav[m][bj][n];
;                             f32x4 ea;
;                             ea[0] = __expf(-__uint_as_float((unsigned)(wa & 0xffffull) << 16)); ea[1] = __expf(-__uint_as_float((unsigned)((wa >> 16) & 0xffffull) << 16));
;                             ea[2] = __expf(-__uint_as_float((unsigned)((wa >> 32) & 0xffffull) << 16)); ea[3] = __expf(-__uint_as_float((unsigned)((wa >> 48) & 0xffffull) << 16));
; #pragma unroll
;                             for (int e_ = 0; e_ < 4; ++e_) acc[ai][bj][m][n][e_] *= (1.0f + eb[e_]) * __builtin_amdgcn_rcpf(1.0f + ea[e_]);
;                         } else {
;                             f32x4 o;
; #pragma unroll
;                             for (int e_ = 0; e_ < 4; ++e_) o[e_] = acc[ai][bj][m][n][e_] * __builtin_amdgcn_rcpf(1.0f + eb[e_]);
;                             *(unsigned long long*)(merged + off + bj * HALF + 16 * n) = (unsigned long long)cvt_pk_bf16(o[0], o[1]) | ((unsigned long long)cvt_pk_bf16(o[2], o[3]) << 32);
.LBB0_1059:
	s_waitcnt vmcnt(3)
	v_lshlrev_b32_e32 v1, 16, v158
	v_max_f32_e32 v1, v1, v1
	v_max_f32_e32 v1, 0xc2700000, v1
	v_mul_f32_e32 v1, 0xbfb8aa3b, v1
	v_lshlrev_b64 v[162:163], 11, v[160:161]
	v_exp_f32_e32 v160, v1
	v_and_b32_e32 v1, 0xffff0000, v158
	v_max_f32_e32 v1, v1, v1
	v_max_f32_e32 v1, 0xc2700000, v1
	v_mul_f32_e32 v1, 0xbfb8aa3b, v1
	v_exp_f32_e32 v161, v1
	v_alignbit_b32 v1, v159, v158, 16
	v_and_b32_e32 v1, 0xffff0000, v1
	v_max_f32_e32 v1, v1, v1
	v_max_f32_e32 v1, 0xc2700000, v1
	v_mul_f32_e32 v1, 0xbfb8aa3b, v1
	v_exp_f32_e32 v158, v1
	v_and_b32_e32 v1, 0xffff0000, v159
	v_max_f32_e32 v1, v1, v1
	v_max_f32_e32 v1, 0xc2700000, v1
	v_mul_f32_e32 v1, 0xbfb8aa3b, v1
	v_exp_f32_e32 v159, v1
	v_lshl_add_u64 v[162:163], s[14:15], 0, v[162:163]
	s_mov_b64 s[6:7], -1
	s_and_b64 vcc, exec, s[4:5]
	v_lshl_add_u64 v[2:3], v[2:3], 1, v[162:163]
	s_cbranch_vccnz .LBB0_1061
	v_add_f32_e32 v162, 1.0, v161
	v_add_f32_e32 v163, 1.0, v158
	v_add_f32_e32 v1, 1.0, v160
	v_rcp_f32_e32 v162, v162
	v_rcp_f32_e32 v163, v163
	v_add_f32_e32 v164, 1.0, v159
	v_rcp_f32_e32 v1, v1
	v_rcp_f32_e32 v164, v164
	v_mul_f32_e32 v162, v41, v162
	v_mul_f32_e32 v163, v42, v163
	s_mov_b64 s[6:7], 0
	v_mul_f32_e32 v1, v40, v1
	v_mul_f32_e32 v164, v43, v164
	v_cvt_pk_bf16_f32 v162, v1, v162
	v_cvt_pk_bf16_f32 v163, v163, v164
	v_and_b32_e32 v244, 48, v254
	v_mov_b32_e32 v245, 0
	v_lshrrev_b32_e32 v244, 1, v244
	v_mov_b32_e32 v240, v162
	v_mov_b32_e32 v241, v163

; __device__ __forceinline__ unsigned cvt_pk_bf16(float lo, float hi) { unsigned r; asm volatile("v_cvt_pk_bf16_f32 %0, %1, %2" : "=v"(r) : "v"(lo), "v"(hi)); return r; }
;     __device__ __forceinline__ void operator()(f32x4 (&acc)[2][2][4][2], const Unit& u, int wr, int wc, int fr, int fq) const {
;     ...
;                         const unsigned long long wb = wbv[m][bj][n];
;                         f32x4 eb;
;                         eb[0] = __expf(-fmaxf(__uint_as_float((unsigned)(wb & 0xffffull) << 16), -60.f)); eb[1] = __expf(-fmaxf(__uint_as_float((unsigned)((wb >> 16) & 0xffffull) << 16), -60.f));
;                         eb[2] = __expf(-fmaxf(__uint_as_float((unsigned)((wb >> 32) & 0xffffull) << 16), -60.f)); eb[3] = __expf(-fmaxf(__uint_as_float((unsigned)((wb >> 48) & 0xffffull) << 16), -60.f));
;                         if (u.kh == 0) {
;                             const unsigned long long wa = wav[m][bj][n];
;                             f32x4 ea;
;                             ea[0] = __expf(-__uint_as_float((unsigned)(wa & 0xffffull) << 16)); ea[1] = __expf(-__uint_as_float((unsigned)((wa >> 16) & 0xffffull) << 16));
;                             ea[2] = __expf(-__uint_as_float((unsigned)((wa >> 32) & 0xffffull) << 16)); ea[3] = __expf(-__uint_as_float((unsigned)((wa >> 48) & 0xffffull) << 16));
; #pragma unroll
;                             for (int e_ = 0; e_ < 4; ++e_) acc[ai][bj][m][n][e_] *= (1.0f + eb[e_]) * __builtin_amdgcn_rcpf(1.0f + ea[e_]);
;                         } else {
;                             f32x4 o;
; #pragma unroll
;                             for (int e_ = 0; e_ < 4; ++e_) o[e_] = acc[ai][bj][m][n][e_] * __builtin_amdgcn_rcpf(1.0f + eb[e_]);
;                             *(unsigned long long*)(merged + off + bj * HALF + 16 * n) = (unsigned long long)cvt_pk_bf16(o[0], o[1]) | ((unsigned long long)cvt_pk_bf16(o[2], o[3]) << 32);
.LBB0_1063:
	s_waitcnt vmcnt(2)
	v_lshlrev_b32_e32 v1, 16, v154
	v_max_f32_e32 v1, v1, v1
	v_max_f32_e32 v1, 0xc2700000, v1
	v_mul_f32_e32 v1, 0xbfb8aa3b, v1
	v_exp_f32_e32 v156, v1
	v_and_b32_e32 v1, 0xffff0000, v154
	v_max_f32_e32 v1, v1, v1
	v_max_f32_e32 v1, 0xc2700000, v1
	v_mul_f32_e32 v1, 0xbfb8aa3b, v1
	v_exp_f32_e32 v157, v1
	v_alignbit_b32 v1, v155, v154, 16
	v_and_b32_e32 v1, 0xffff0000, v1
	v_max_f32_e32 v1, v1, v1
	v_max_f32_e32 v1, 0xc2700000, v1
	v_mul_f32_e32 v1, 0xbfb8aa3b, v1
	v_exp_f32_e32 v154, v1
	v_and_b32_e32 v1, 0xffff0000, v155
	v_max_f32_e32 v1, v1, v1
	v_max_f32_e32 v1, 0xc2700000, v1
	v_mul_f32_e32 v1, 0xbfb8aa3b, v1
	v_exp_f32_e32 v155, v1
	s_and_b64 vcc, exec, s[4:5]
	s_mov_b64 s[6:7], -1
	s_cbranch_vccnz .LBB0_1065
	v_add_f32_e32 v158, 1.0, v157
	v_add_f32_e32 v159, 1.0, v154
	v_add_f32_e32 v1, 1.0, v156
	v_rcp_f32_e32 v158, v158
	v_rcp_f32_e32 v159, v159
	v_add_f32_e32 v160, 1.0, v155
	v_rcp_f32_e32 v1, v1
	v_rcp_f32_e32 v160, v160
	v_mul_f32_e32 v158, v37, v158
	v_mul_f32_e32 v159, v38, v159
	s_mov_b64 s[6:7], 0
	v_mul_f32_e32 v1, v36, v1
	v_mul_f32_e32 v160, v39, v160
	v_cvt_pk_bf16_f32 v158, v1, v158
	v_cvt_pk_bf16_f32 v159, v159, v160
	v_mov_b32_e32 v242, v158
	v_mov_b32_e32 v243, v159
	v_lshl_add_u64 v[246:247], v[2:3], 0, v[244:245]
	s_nop 0
	v_permlane32_swap_b32_e32 v240, v242
	v_permlane32_swap_b32_e32 v241, v243
	s_nop 0
	v_permlane16_swap_b32_e32 v240, v242
	v_permlane16_swap_b32_e32 v241, v243
	s_nop 1
	global_store_dwordx4 v[246:247], v[240:243], off

; __device__ __forceinline__ unsigned cvt_pk_bf16(float lo, float hi) { unsigned r; asm volatile("v_cvt_pk_bf16_f32 %0, %1, %2" : "=v"(r) : "v"(lo), "v"(hi)); return r; }
;     __device__ __forceinline__ void operator()(f32x4 (&acc)[2][2][4][2], const Unit& u, int wr, int wc, int fr, int fq) const {
;     ...
;                         const unsigned long long wb = wbv[m][bj][n];
;                         f32x4 eb;
;                         eb[0] = __expf(-fmaxf(__uint_as_float((unsigned)(wb & 0xffffull) << 16), -60.f)); eb[1] = __expf(-fmaxf(__uint_as_float((unsigned)((wb >> 16) & 0xffffull) << 16), -60.f));
;                         eb[2] = __expf(-fmaxf(__uint_as_float((unsigned)((wb >> 32) & 0xffffull) << 16), -60.f)); eb[3] = __expf(-fmaxf(__uint_as_float((unsigned)((wb >> 48) & 0xffffull) << 16), -60.f));
;                         if (u.kh == 0) {
;                             const unsigned long long wa = wav[m][bj][n];
;                             f32x4 ea;
;                             ea[0] = __expf(-__uint_as_float((unsigned)(wa & 0xffffull) << 16)); ea[1] = __expf(-__uint_as_float((unsigned)((wa >> 16) & 0xffffull) << 16));
;                             ea[2] = __expf(-__uint_as_float((unsigned)((wa >> 32) & 0xffffull) << 16)); ea[3] = __expf(-__uint_as_float((unsigned)((wa >> 48) & 0xffffull) << 16));
; #pragma unroll
;                             for (int e_ = 0; e_ < 4; ++e_) acc[ai][bj][m][n][e_] *= (1.0f + eb[e_]) * __builtin_amdgcn_rcpf(1.0f + ea[e_]);
;                         } else {
;                             f32x4 o;
; #pragma unroll
;                             for (int e_ = 0; e_ < 4; ++e_) o[e_] = acc[ai][bj][m][n][e_] * __builtin_amdgcn_rcpf(1.0f + eb[e_]);
;                             *(unsigned long long*)(merged + off + bj * HALF + 16 * n) = (unsigned long long)cvt_pk_bf16(o[0], o[1]) | ((unsigned long long)cvt_pk_bf16(o[2], o[3]) << 32);
.LBB0_1067:
	s_waitcnt vmcnt(1)
	v_lshlrev_b32_e32 v1, 16, v150
	v_max_f32_e32 v1, v1, v1
	v_max_f32_e32 v1, 0xc2700000, v1
	v_mul_f32_e32 v1, 0xbfb8aa3b, v1
	v_exp_f32_e32 v152, v1
	v_and_b32_e32 v1, 0xffff0000, v150
	v_max_f32_e32 v1, v1, v1
	v_max_f32_e32 v1, 0xc2700000, v1
	v_mul_f32_e32 v1, 0xbfb8aa3b, v1
	v_exp_f32_e32 v153, v1
	v_alignbit_b32 v1, v151, v150, 16
	v_and_b32_e32 v1, 0xffff0000, v1
	v_max_f32_e32 v1, v1, v1
	v_max_f32_e32 v1, 0xc2700000, v1
	v_mul_f32_e32 v1, 0xbfb8aa3b, v1
	v_exp_f32_e32 v150, v1
	v_and_b32_e32 v1, 0xffff0000, v151
	v_max_f32_e32 v1, v1, v1
	v_max_f32_e32 v1, 0xc2700000, v1
	v_mul_f32_e32 v1, 0xbfb8aa3b, v1
	v_exp_f32_e32 v151, v1
	s_and_b64 vcc, exec, s[4:5]
	s_mov_b64 s[6:7], -1
	s_cbranch_vccnz .LBB0_1069
	v_add_f32_e32 v154, 1.0, v153
	v_add_f32_e32 v155, 1.0, v150
	v_add_f32_e32 v1, 1.0, v152
	v_rcp_f32_e32 v154, v154
	v_rcp_f32_e32 v155, v155
	v_add_f32_e32 v156, 1.0, v151
	v_rcp_f32_e32 v1, v1
	v_rcp_f32_e32 v156, v156
	v_mul_f32_e32 v154, v9, v154
	v_mul_f32_e32 v155, v10, v155
	s_mov_b64 s[6:7], 0
	v_mul_f32_e32 v1, v8, v1
	v_mul_f32_e32 v156, v11, v156
	v_cvt_pk_bf16_f32 v154, v1, v154
	v_cvt_pk_bf16_f32 v155, v155, v156
	v_mov_b32_e32 v240, v154
	v_mov_b32_e32 v241, v155

; __device__ __forceinline__ unsigned cvt_pk_bf16(float lo, float hi) { unsigned r; asm volatile("v_cvt_pk_bf16_f32 %0, %1, %2" : "=v"(r) : "v"(lo), "v"(hi)); return r; }
;     __device__ __forceinline__ void operator()(f32x4 (&acc)[2][2][4][2], const Unit& u, int wr, int wc, int fr, int fq) const {
;     ...
;                         const unsigned long long wb = wbv[m][bj][n];
;                         f32x4 eb;
;                         eb[0] = __expf(-fmaxf(__uint_as_float((unsigned)(wb & 0xffffull) << 16), -60.f)); eb[1] = __expf(-fmaxf(__uint_as_float((unsigned)((wb >> 16) & 0xffffull) << 16), -60.f));
;                         eb[2] = __expf(-fmaxf(__uint_as_float((unsigned)((wb >> 32) & 0xffffull) << 16), -60.f)); eb[3] = __expf(-fmaxf(__uint_as_float((unsigned)((wb >> 48) & 0xffffull) << 16), -60.f));
;                         if (u.kh == 0) {
;                             const unsigned long long wa = wav[m][bj][n];
;                             f32x4 ea;
;                             ea[0] = __expf(-__uint_as_float((unsigned)(wa & 0xffffull) << 16)); ea[1] = __expf(-__uint_as_float((unsigned)((wa >> 16) & 0xffffull) << 16));
;                             ea[2] = __expf(-__uint_as_float((unsigned)((wa >> 32) & 0xffffull) << 16)); ea[3] = __expf(-__uint_as_float((unsigned)((wa >> 48) & 0xffffull) << 16));
; #pragma unroll
;                             for (int e_ = 0; e_ < 4; ++e_) acc[ai][bj][m][n][e_] *= (1.0f + eb[e_]) * __builtin_amdgcn_rcpf(1.0f + ea[e_]);
;                         } else {
;                             f32x4 o;
; #pragma unroll
;                             for (int e_ = 0; e_ < 4; ++e_) o[e_] = acc[ai][bj][m][n][e_] * __builtin_amdgcn_rcpf(1.0f + eb[e_]);
;                             *(unsigned long long*)(merged + off + bj * HALF + 16 * n) = (unsigned long long)cvt_pk_bf16(o[0], o[1]) | ((unsigned long long)cvt_pk_bf16(o[2], o[3]) << 32);
.LBB0_1071:
	s_waitcnt vmcnt(0)
	v_lshlrev_b32_e32 v1, 16, v146
	v_max_f32_e32 v1, v1, v1
	v_max_f32_e32 v1, 0xc2700000, v1
	v_mul_f32_e32 v1, 0xbfb8aa3b, v1
	v_exp_f32_e32 v148, v1
	v_and_b32_e32 v1, 0xffff0000, v146
	v_max_f32_e32 v1, v1, v1
	v_max_f32_e32 v1, 0xc2700000, v1
	v_mul_f32_e32 v1, 0xbfb8aa3b, v1
	v_exp_f32_e32 v149, v1
	v_alignbit_b32 v1, v147, v146, 16
	v_and_b32_e32 v1, 0xffff0000, v1
	v_max_f32_e32 v1, v1, v1
	v_max_f32_e32 v1, 0xc2700000, v1
	v_mul_f32_e32 v1, 0xbfb8aa3b, v1
	v_exp_f32_e32 v146, v1
	v_and_b32_e32 v1, 0xffff0000, v147
	v_max_f32_e32 v1, v1, v1
	v_max_f32_e32 v1, 0xc2700000, v1
	v_mul_f32_e32 v1, 0xbfb8aa3b, v1
	v_exp_f32_e32 v147, v1
	s_and_b64 vcc, exec, s[4:5]
	s_mov_b64 s[4:5], -1
	s_cbranch_vccnz .LBB0_1074
	v_add_f32_e32 v150, 1.0, v149
	v_add_f32_e32 v151, 1.0, v146
	v_add_f32_e32 v1, 1.0, v148
	v_rcp_f32_e32 v150, v150
	v_rcp_f32_e32 v151, v151
	v_add_f32_e32 v152, 1.0, v147
	v_rcp_f32_e32 v1, v1
	v_rcp_f32_e32 v152, v152
	v_mul_f32_e32 v150, v5, v150
	v_mul_f32_e32 v151, v6, v151
	v_mul_f32_e32 v1, v4, v1
	v_mul_f32_e32 v152, v7, v152
	v_cvt_pk_bf16_f32 v150, v1, v150
	v_cvt_pk_bf16_f32 v151, v151, v152
	v_mov_b32_e32 v242, v150
	v_mov_b32_e32 v243, v151
	v_lshl_add_u64 v[246:247], v[2:3], 0, v[244:245]
	s_nop 0
	v_permlane32_swap_b32_e32 v240, v242
	v_permlane32_swap_b32_e32 v241, v243
	s_nop 0
	v_permlane16_swap_b32_e32 v240, v242
	v_permlane16_swap_b32_e32 v241, v243
	s_nop 1
	global_store_dwordx4 v[246:247], v[240:243], off offset:256
	s_cbranch_execz .LBB0_1075

;     __device__ __forceinline__ void operator()(const f32x4 (&acc)[2][2][4][2], const Unit& u, int wr, int wc, int fr, int fq) const {
;         const int row0 = u.pm * BM + wr * 64 + fr, col0 = u.pn * BM + wc * 32 + 4 * fq;
;         const float* gp = gate + ((u.pm * BM) >> 12) * 6144 + col0;
;         f32x4 gv[2][2];
; #pragma unroll
;         for (int bj = 0; bj < 2; ++bj)
; #pragma unroll
;             for (int n = 0; n < 2; ++n) gv[bj][n] = *(const f32x4*)(gp + bj * HALF + 16 * n);
; #pragma unroll
;         for (int ai = 0; ai < 2; ++ai) {
;             f32x4 bv[4][2][2]; unsigned long long bw[4][2][2];
; #pragma unroll
;             for (int m = 0; m < 4; ++m) { const size_t off = (size_t)(row0 + ai * HALF + m * 16) * 1024 + col0;
; #pragma unroll
;                 for (int bj = 0; bj < 2; ++bj)
; #pragma unroll
;                     for (int n = 0; n < 2; ++n) {
;                         if (BASE_BF16) bw[m][bj][n] = __builtin_nontemporal_load((const unsigned long long*)((const bf16_t*)base + off + bj * HALF + 16 * n));
;                         else bv[m][bj][n] = __builtin_nontemporal_load((const f32x4*)((const float*)base + off + bj * HALF + 16 * n)); } }
;             asm volatile("" ::: "memory");
; #pragma unroll
;             for (int m = 0; m < 4; ++m) { const size_t off = (size_t)(row0 + ai * HALF + m * 16) * 1024 + col0;
; #pragma unroll
;                 for (int bj = 0; bj < 2; ++bj)
; #pragma unroll
;                     for (int n = 0; n < 2; ++n) {
;                         f32x4 b4;
;                         if (BASE_BF16) { const unsigned long long w = bw[m][bj][n];
;                             b4 = (f32x4){__uint_as_float((unsigned)(w & 0xffffull) << 16), __uint_as_float((unsigned)((w >> 16) & 0xffffull) << 16),
;                                          __uint_as_float((unsigned)((w >> 32) & 0xffffull) << 16), __uint_as_float((unsigned)((w >> 48) & 0xffffull) << 16)}; }
;                         else b4 = bv[m][bj][n];
;                         const f32x4 o = b4 + gv[bj][n] * acc[ai][bj][m][n];
;                         if (OUT_BF16) *(unsigned long long*)((bf16_t*)out + off + bj * HALF + 16 * n) = (unsigned long long)cvt_pk_bf16(o[0], o[1]) | ((unsigned long long)cvt_pk_bf16(o[2], o[3]) << 32);
;                         else *(f32x4*)((float*)out + off + bj * HALF + 16 * n) = o; } }
.LBB0_1189:
	v_lshl_or_b32 v160, s3, 8, v170
	s_lshr_b32 s3, s20, 4
	s_mul_i32 s22, s3, 0x1800
	s_ashr_i32 s23, s22, 31
	s_lshl_b64 s[22:23], s[22:23], 2
	s_add_u32 s22, s56, s22
	v_ashrrev_i32_e32 v161, 31, v160
	v_lshl_add_u32 v164, s20, 8, v168
	s_addc_u32 s23, s57, s23
	v_lshlrev_b64 v[144:145], 2, v[160:161]
	v_ashrrev_i32_e32 v165, 31, v164
	v_lshl_add_u64 v[128:129], s[22:23], 0, v[144:145]
	v_lshl_add_u64 v[162:163], s[52:53], 0, v[144:145]
	v_lshlrev_b64 v[144:145], 12, v[164:165]
	v_or_b32_e32 v222, 16, v164
	v_lshl_add_u64 v[144:145], v[162:163], 0, v[144:145]
	v_ashrrev_i32_e32 v223, 31, v222
	global_load_dwordx4 v[140:143], v[128:129], off
	global_load_dwordx4 v[136:139], v[128:129], off offset:64
	global_load_dwordx4 v[132:135], v[128:129], off offset:512
	s_nop 0
	global_load_dwordx4 v[128:131], v[128:129], off offset:576
	s_nop 0
	global_load_dwordx4 v[174:177], v[144:145], off nt
	global_load_dwordx4 v[178:181], v[144:145], off offset:64 nt
	global_load_dwordx4 v[182:185], v[144:145], off offset:512 nt
	global_load_dwordx4 v[186:189], v[144:145], off offset:576 nt
	v_lshlrev_b64 v[144:145], 12, v[222:223]
	v_or_b32_e32 v228, 32, v164
	v_lshl_add_u64 v[144:145], v[162:163], 0, v[144:145]
	v_ashrrev_i32_e32 v229, 31, v228
	global_load_dwordx4 v[190:193], v[144:145], off nt
	global_load_dwordx4 v[194:197], v[144:145], off offset:64 nt
	global_load_dwordx4 v[198:201], v[144:145], off offset:512 nt
	global_load_dwordx4 v[202:205], v[144:145], off offset:576 nt
	v_lshlrev_b64 v[144:145], 12, v[228:229]
	v_lshl_add_u64 v[144:145], v[162:163], 0, v[144:145]
	global_load_dwordx4 v[206:209], v[144:145], off nt
	global_load_dwordx4 v[210:213], v[144:145], off offset:64 nt
	global_load_dwordx4 v[214:217], v[144:145], off offset:512 nt
	global_load_dwordx4 v[218:221], v[144:145], off offset:576 nt
	v_or_b32_e32 v166, 48, v164
	v_ashrrev_i32_e32 v167, 31, v166
	v_lshlrev_b64 v[144:145], 12, v[166:167]
	v_lshlrev_b64 v[230:231], 11, v[164:165]
	v_lshl_add_u64 v[232:233], v[162:163], 0, v[144:145]
	v_lshlrev_b64 v[160:161], 1, v[160:161]
	v_lshl_add_u64 v[230:231], s[6:7], 0, v[230:231]
	global_load_dwordx4 v[144:147], v[232:233], off nt
	global_load_dwordx4 v[224:227], v[232:233], off offset:64 nt
	v_lshlrev_b64 v[236:237], 11, v[228:229]
	v_lshl_add_u64 v[238:239], v[230:231], 0, v[160:161]
	global_load_dwordx4 v[228:231], v[232:233], off offset:512 nt
	v_lshlrev_b64 v[222:223], 11, v[222:223]
	global_load_dwordx4 v[232:235], v[232:233], off offset:576 nt
	v_lshl_add_u64 v[222:223], s[6:7], 0, v[222:223]
	v_lshl_add_u64 v[222:223], v[222:223], 0, v[160:161]
	s_andn2_b64 vcc, exec, s[0:1]
	s_mov_b64 s[0:1], -1
	s_waitcnt vmcnt(0)
	v_pk_fma_f32 v[124:125], v[124:125], v[140:141], v[174:175]
	v_pk_fma_f32 v[120:121], v[120:121], v[136:137], v[178:179]
	v_pk_fma_f32 v[108:109], v[108:109], v[132:133], v[182:183]
	v_pk_fma_f32 v[104:105], v[104:105], v[128:129], v[186:187]
	v_pk_fma_f32 v[126:127], v[126:127], v[142:143], v[176:177]
	v_pk_fma_f32 v[122:123], v[122:123], v[138:139], v[180:181]
	v_pk_fma_f32 v[110:111], v[110:111], v[134:135], v[184:185]
	v_pk_fma_f32 v[106:107], v[106:107], v[130:131], v[188:189]
	v_cvt_pk_bf16_f32 v124, v124, v125
	v_cvt_pk_bf16_f32 v125, v126, v127
	v_and_b32_e32 v244, 48, v254
	v_mov_b32_e32 v245, 0
	v_lshrrev_b32_e32 v244, 1, v244
	v_mov_b32_e32 v240, v124
	v_mov_b32_e32 v241, v125
	v_cvt_pk_bf16_f32 v120, v120, v121
	v_cvt_pk_bf16_f32 v121, v122, v123
	v_mov_b32_e32 v242, v120
	v_mov_b32_e32 v243, v121
	v_lshl_add_u64 v[246:247], v[238:239], 0, v[244:245]
	s_nop 0
	v_permlane32_swap_b32_e32 v240, v242
	v_permlane32_swap_b32_e32 v241, v243
	s_nop 0
	v_permlane16_swap_b32_e32 v240, v242
	v_permlane16_swap_b32_e32 v241, v243
	s_nop 1
	global_store_dwordx4 v[246:247], v[240:243], off
	v_cvt_pk_bf16_f32 v108, v108, v109
	v_cvt_pk_bf16_f32 v109, v110, v111
	v_mov_b32_e32 v240, v108
	v_mov_b32_e32 v241, v109
	v_cvt_pk_bf16_f32 v104, v104, v105
	v_cvt_pk_bf16_f32 v105, v106, v107
	v_pk_fma_f32 v[118:119], v[118:119], v[142:143], v[192:193]
	v_pk_fma_f32 v[116:117], v[116:117], v[140:141], v[190:191]
	v_pk_fma_f32 v[100:101], v[100:101], v[132:133], v[198:199]
	v_pk_fma_f32 v[96:97], v[96:97], v[128:129], v[202:203]
	v_pk_fma_f32 v[94:95], v[94:95], v[142:143], v[208:209]
	v_mov_b32_e32 v242, v104
	v_mov_b32_e32 v243, v105
	v_lshl_add_u64 v[246:247], v[238:239], 0, v[244:245]
	s_nop 0
	v_permlane32_swap_b32_e32 v240, v242
	v_permlane32_swap_b32_e32 v241, v243
	s_nop 0
	v_permlane16_swap_b32_e32 v240, v242
	v_permlane16_swap_b32_e32 v241, v243
	s_nop 1
	global_store_dwordx4 v[246:247], v[240:243], off offset:256
	v_cvt_pk_bf16_f32 v104, v116, v117
	v_cvt_pk_bf16_f32 v105, v118, v119
	v_pk_fma_f32 v[92:93], v[92:93], v[140:141], v[206:207]
	v_pk_fma_f32 v[114:115], v[114:115], v[138:139], v[196:197]
	v_pk_fma_f32 v[112:113], v[112:113], v[136:137], v[194:195]
	v_pk_fma_f32 v[102:103], v[102:103], v[134:135], v[200:201]
	v_pk_fma_f32 v[98:99], v[98:99], v[130:131], v[204:205]
	v_mov_b32_e32 v240, v104
	v_mov_b32_e32 v241, v105
	v_cvt_pk_bf16_f32 v104, v112, v113
	v_cvt_pk_bf16_f32 v105, v114, v115
	v_mov_b32_e32 v242, v104
	v_mov_b32_e32 v243, v105
	v_lshl_add_u64 v[246:247], v[222:223], 0, v[244:245]
	s_nop 0
	v_permlane32_swap_b32_e32 v240, v242
	v_permlane32_swap_b32_e32 v241, v243
	s_nop 0
	v_permlane16_swap_b32_e32 v240, v242
	v_permlane16_swap_b32_e32 v241, v243
	s_nop 1
	global_store_dwordx4 v[246:247], v[240:243], off
	v_cvt_pk_bf16_f32 v100, v100, v101
	v_cvt_pk_bf16_f32 v101, v102, v103
	v_mov_b32_e32 v240, v100
	v_mov_b32_e32 v241, v101
	v_cvt_pk_bf16_f32 v96, v96, v97
	v_cvt_pk_bf16_f32 v97, v98, v99
; __device__ __forceinline__ unsigned cvt_pk_bf16(float lo, float hi) { unsigned r; asm volatile("v_cvt_pk_bf16_f32 %0, %1, %2" : "=v"(r) : "v"(lo), "v"(hi)); return r; }
;     __device__ __forceinline__ void operator()(const f32x4 (&acc)[2][2][4][2], const Unit& u, int wr, int wc, int fr, int fq) const {
;     ...
;         for (int ai = 0; ai < 2; ++ai) {
;             f32x4 bv[4][2][2]; unsigned long long bw[4][2][2];
; #pragma unroll
;             for (int m = 0; m < 4; ++m) { const size_t off = (size_t)(row0 + ai * HALF + m * 16) * 1024 + col0;
; #pragma unroll
;                 for (int bj = 0; bj < 2; ++bj)
; #pragma unroll
;                     for (int n = 0; n < 2; ++n) {
;                         if (BASE_BF16) bw[m][bj][n] = __builtin_nontemporal_load((const unsigned long long*)((const bf16_t*)base + off + bj * HALF + 16 * n));
;                         else bv[m][bj][n] = __builtin_nontemporal_load((const f32x4*)((const float*)base + off + bj * HALF + 16 * n)); } }
;             asm volatile("" ::: "memory");
; #pragma unroll
;             for (int m = 0; m < 4; ++m) { const size_t off = (size_t)(row0 + ai * HALF + m * 16) * 1024 + col0;
; #pragma unroll
;                 for (int bj = 0; bj < 2; ++bj)
; #pragma unroll
;                     for (int n = 0; n < 2; ++n) {
;                         f32x4 b4;
;                         if (BASE_BF16) { const unsigned long long w = bw[m][bj][n];
;                             b4 = (f32x4){__uint_as_float((unsigned)(w & 0xffffull) << 16), __uint_as_float((unsigned)((w >> 16) & 0xffffull) << 16),
;                                          __uint_as_float((unsigned)((w >> 32) & 0xffffull) << 16), __uint_as_float((unsigned)((w >> 48) & 0xffffull) << 16)}; }
;                         else b4 = bv[m][bj][n];
;                         const f32x4 o = b4 + gv[bj][n] * acc[ai][bj][m][n];
;                         if (OUT_BF16) *(unsigned long long*)((bf16_t*)out + off + bj * HALF + 16 * n) = (unsigned long long)cvt_pk_bf16(o[0], o[1]) | ((unsigned long long)cvt_pk_bf16(o[2], o[3]) << 32);
;                         else *(f32x4*)((float*)out + off + bj * HALF + 16 * n) = o; } }
	v_mov_b32_e32 v242, v96
	v_mov_b32_e32 v243, v97
	v_lshl_add_u64 v[246:247], v[222:223], 0, v[244:245]
	s_nop 0
	v_permlane32_swap_b32_e32 v240, v242
	v_permlane32_swap_b32_e32 v241, v243
	s_nop 0
	v_permlane16_swap_b32_e32 v240, v242
	v_permlane16_swap_b32_e32 v241, v243
	s_nop 1
	global_store_dwordx4 v[246:247], v[240:243], off offset:256
	v_cvt_pk_bf16_f32 v92, v92, v93
	v_cvt_pk_bf16_f32 v93, v94, v95
	v_lshl_add_u64 v[94:95], s[6:7], 0, v[236:237]
	v_lshl_add_u64 v[94:95], v[94:95], 0, v[160:161]
	v_pk_fma_f32 v[88:89], v[88:89], v[136:137], v[210:211]
	v_pk_fma_f32 v[84:85], v[84:85], v[132:133], v[214:215]
	v_pk_fma_f32 v[76:77], v[76:77], v[128:129], v[218:219]
	v_mov_b32_e32 v240, v92
	v_mov_b32_e32 v241, v93
	v_pk_fma_f32 v[90:91], v[90:91], v[138:139], v[212:213]
	v_cvt_pk_bf16_f32 v88, v88, v89
	v_pk_fma_f32 v[86:87], v[86:87], v[134:135], v[216:217]
	v_cvt_pk_bf16_f32 v89, v90, v91
	v_mov_b32_e32 v242, v88
	v_mov_b32_e32 v243, v89
	v_lshl_add_u64 v[246:247], v[94:95], 0, v[244:245]
	s_nop 0
	v_permlane32_swap_b32_e32 v240, v242
	v_permlane32_swap_b32_e32 v241, v243
	s_nop 0
	v_permlane16_swap_b32_e32 v240, v242
	v_permlane16_swap_b32_e32 v241, v243
	s_nop 1
	global_store_dwordx4 v[246:247], v[240:243], off
	v_cvt_pk_bf16_f32 v84, v84, v85
	v_cvt_pk_bf16_f32 v85, v86, v87
	v_mov_b32_e32 v240, v84
	v_mov_b32_e32 v241, v85
	v_pk_fma_f32 v[78:79], v[78:79], v[130:131], v[220:221]
	v_cvt_pk_bf16_f32 v76, v76, v77
	v_pk_fma_f32 v[80:81], v[80:81], v[140:141], v[144:145]
	v_cvt_pk_bf16_f32 v77, v78, v79
	v_mov_b32_e32 v242, v76
	v_mov_b32_e32 v243, v77
	v_lshl_add_u64 v[246:247], v[94:95], 0, v[244:245]
	s_nop 0
	v_permlane32_swap_b32_e32 v240, v242
	v_permlane32_swap_b32_e32 v241, v243
	s_nop 0
	v_permlane16_swap_b32_e32 v240, v242
	v_permlane16_swap_b32_e32 v241, v243
	s_nop 1
	global_store_dwordx4 v[246:247], v[240:243], off offset:256
	v_lshlrev_b64 v[76:77], 11, v[166:167]
	v_lshl_add_u64 v[76:77], s[6:7], 0, v[76:77]
	v_lshl_add_u64 v[76:77], v[76:77], 0, v[160:161]
	v_pk_fma_f32 v[72:73], v[72:73], v[136:137], v[224:225]
	v_pk_fma_f32 v[68:69], v[68:69], v[132:133], v[228:229]
	v_pk_fma_f32 v[64:65], v[64:65], v[128:129], v[232:233]
	v_add_u32_e32 v116, 0x80, v164
	v_pk_fma_f32 v[78:79], v[82:83], v[142:143], v[146:147]
	v_cvt_pk_bf16_f32 v80, v80, v81
	v_pk_fma_f32 v[74:75], v[74:75], v[138:139], v[226:227]
	v_cvt_pk_bf16_f32 v81, v78, v79
	v_mov_b32_e32 v240, v80
	v_mov_b32_e32 v241, v81
	v_cvt_pk_bf16_f32 v72, v72, v73
	v_cvt_pk_bf16_f32 v73, v74, v75
	v_mov_b32_e32 v242, v72
	v_mov_b32_e32 v243, v73
	v_lshl_add_u64 v[246:247], v[76:77], 0, v[244:245]
	s_nop 0
	v_permlane32_swap_b32_e32 v240, v242
	v_permlane32_swap_b32_e32 v241, v243
	s_nop 0
	v_permlane16_swap_b32_e32 v240, v242
	v_permlane16_swap_b32_e32 v241, v243
	s_nop 1
	global_store_dwordx4 v[246:247], v[240:243], off
	v_pk_fma_f32 v[70:71], v[70:71], v[134:135], v[230:231]
	v_cvt_pk_bf16_f32 v68, v68, v69
	v_pk_fma_f32 v[66:67], v[66:67], v[130:131], v[234:235]
	v_cvt_pk_bf16_f32 v69, v70, v71
	v_mov_b32_e32 v240, v68
	v_mov_b32_e32 v241, v69
	v_cvt_pk_bf16_f32 v64, v64, v65
	v_cvt_pk_bf16_f32 v65, v66, v67
	v_ashrrev_i32_e32 v117, 31, v116
	v_mov_b32_e32 v242, v64
	v_mov_b32_e32 v243, v65
	v_lshl_add_u64 v[246:247], v[76:77], 0, v[244:245]
	s_nop 0
	v_permlane32_swap_b32_e32 v240, v242
	v_permlane32_swap_b32_e32 v241, v243
	s_nop 0
	v_permlane16_swap_b32_e32 v240, v242
	v_permlane16_swap_b32_e32 v241, v243
	s_nop 1
	global_store_dwordx4 v[246:247], v[240:243], off offset:256
	v_lshlrev_b64 v[64:65], 12, v[116:117]
	v_lshl_add_u64 v[76:77], v[162:163], 0, v[64:65]
	global_load_dwordx4 v[64:67], v[76:77], off nt
	global_load_dwordx4 v[68:71], v[76:77], off offset:64 nt
	global_load_dwordx4 v[72:75], v[76:77], off offset:512 nt
	s_nop 0
	global_load_dwordx4 v[76:79], v[76:77], off offset:576 nt
	v_add_u32_e32 v144, 0x90, v164
	v_ashrrev_i32_e32 v145, 31, v144
	v_lshlrev_b64 v[80:81], 12, v[144:145]
	v_lshl_add_u64 v[92:93], v[162:163], 0, v[80:81]
	global_load_dwordx4 v[80:83], v[92:93], off nt
	global_load_dwordx4 v[84:87], v[92:93], off offset:64 nt
	global_load_dwordx4 v[88:91], v[92:93], off offset:512 nt
	s_nop 0
	global_load_dwordx4 v[92:95], v[92:93], off offset:576 nt
	v_add_u32_e32 v146, 0xa0, v164
	v_ashrrev_i32_e32 v147, 31, v146
	v_lshlrev_b64 v[96:97], 12, v[146:147]
	v_lshl_add_u64 v[108:109], v[162:163], 0, v[96:97]
	global_load_dwordx4 v[96:99], v[108:109], off nt
	global_load_dwordx4 v[100:103], v[108:109], off offset:64 nt
	global_load_dwordx4 v[104:107], v[108:109], off offset:512 nt
	s_nop 0
	global_load_dwordx4 v[108:111], v[108:109], off offset:576 nt
	v_add_u32_e32 v164, 0xb0, v164
	v_ashrrev_i32_e32 v165, 31, v164
	v_lshlrev_b64 v[112:113], 12, v[164:165]
	v_lshlrev_b64 v[120:121], 11, v[116:117]
	v_lshl_add_u64 v[124:125], v[162:163], 0, v[112:113]
	v_lshl_add_u64 v[120:121], s[6:7], 0, v[120:121]
	global_load_dwordx4 v[112:115], v[124:125], off nt
	global_load_dwordx4 v[116:119], v[124:125], off offset:64 nt
	v_lshl_add_u64 v[162:163], v[120:121], 0, v[160:161]
	global_load_dwordx4 v[120:123], v[124:125], off offset:512 nt
	s_nop 0
	global_load_dwordx4 v[124:127], v[124:125], off offset:576 nt
	s_waitcnt vmcnt(15)
	v_pk_fma_f32 v[60:61], v[60:61], v[140:141], v[64:65]
	s_waitcnt vmcnt(14)
	v_pk_fma_f32 v[56:57], v[56:57], v[136:137], v[68:69]
	s_waitcnt vmcnt(13)
	v_pk_fma_f32 v[52:53], v[52:53], v[132:133], v[72:73]
	s_waitcnt vmcnt(12)
; __device__ __forceinline__ unsigned cvt_pk_bf16(float lo, float hi) { unsigned r; asm volatile("v_cvt_pk_bf16_f32 %0, %1, %2" : "=v"(r) : "v"(lo), "v"(hi)); return r; }
;     __device__ __forceinline__ void operator()(const f32x4 (&acc)[2][2][4][2], const Unit& u, int wr, int wc, int fr, int fq) const {
;     ...
;             for (int m = 0; m < 4; ++m) { const size_t off = (size_t)(row0 + ai * HALF + m * 16) * 1024 + col0;
; #pragma unroll
;                 for (int bj = 0; bj < 2; ++bj)
; #pragma unroll
;                     for (int n = 0; n < 2; ++n) {
;                         f32x4 b4;
;                         if (BASE_BF16) { const unsigned long long w = bw[m][bj][n];
;                             b4 = (f32x4){__uint_as_float((unsigned)(w & 0xffffull) << 16), __uint_as_float((unsigned)((w >> 16) & 0xffffull) << 16),
;                                          __uint_as_float((unsigned)((w >> 32) & 0xffffull) << 16), __uint_as_float((unsigned)((w >> 48) & 0xffffull) << 16)}; }
;                         else b4 = bv[m][bj][n];
;                         const f32x4 o = b4 + gv[bj][n] * acc[ai][bj][m][n];
;                         if (OUT_BF16) *(unsigned long long*)((bf16_t*)out + off + bj * HALF + 16 * n) = (unsigned long long)cvt_pk_bf16(o[0], o[1]) | ((unsigned long long)cvt_pk_bf16(o[2], o[3]) << 32);
;                         else *(f32x4*)((float*)out + off + bj * HALF + 16 * n) = o; } }
	v_pk_fma_f32 v[44:45], v[44:45], v[128:129], v[76:77]
	v_pk_fma_f32 v[62:63], v[62:63], v[142:143], v[66:67]
	v_pk_fma_f32 v[58:59], v[58:59], v[138:139], v[70:71]
	v_pk_fma_f32 v[54:55], v[54:55], v[134:135], v[74:75]
	v_cvt_pk_bf16_f32 v60, v60, v61
	v_cvt_pk_bf16_f32 v61, v62, v63
	v_mov_b32_e32 v240, v60
	v_mov_b32_e32 v241, v61
	v_cvt_pk_bf16_f32 v56, v56, v57
	v_cvt_pk_bf16_f32 v57, v58, v59
	v_mov_b32_e32 v242, v56
	v_mov_b32_e32 v243, v57
	v_lshl_add_u64 v[246:247], v[162:163], 0, v[244:245]
	s_nop 0
	v_permlane32_swap_b32_e32 v240, v242
	v_permlane32_swap_b32_e32 v241, v243
	s_nop 0
	v_permlane16_swap_b32_e32 v240, v242
	v_permlane16_swap_b32_e32 v241, v243
	s_nop 1
	global_store_dwordx4 v[246:247], v[240:243], off
	v_cvt_pk_bf16_f32 v52, v52, v53
	v_cvt_pk_bf16_f32 v53, v54, v55
	v_mov_b32_e32 v240, v52
	v_mov_b32_e32 v241, v53
	v_pk_fma_f32 v[46:47], v[46:47], v[130:131], v[78:79]
	v_cvt_pk_bf16_f32 v44, v44, v45
	s_waitcnt vmcnt(12)
	v_pk_fma_f32 v[48:49], v[48:49], v[140:141], v[80:81]
	v_cvt_pk_bf16_f32 v45, v46, v47
	v_mov_b32_e32 v242, v44
	v_mov_b32_e32 v243, v45
	v_lshl_add_u64 v[246:247], v[162:163], 0, v[244:245]
	s_nop 0
	v_permlane32_swap_b32_e32 v240, v242
	v_permlane32_swap_b32_e32 v241, v243
	s_nop 0
	v_permlane16_swap_b32_e32 v240, v242
	v_permlane16_swap_b32_e32 v241, v243
	s_nop 1
	global_store_dwordx4 v[246:247], v[240:243], off offset:256
	v_lshlrev_b64 v[44:45], 11, v[144:145]
	v_lshl_add_u64 v[44:45], s[6:7], 0, v[44:45]
	v_lshl_add_u64 v[44:45], v[44:45], 0, v[160:161]
	s_waitcnt vmcnt(12)
	v_pk_fma_f32 v[40:41], v[40:41], v[136:137], v[84:85]
	s_waitcnt vmcnt(11)
	v_pk_fma_f32 v[36:37], v[36:37], v[132:133], v[88:89]
	s_waitcnt vmcnt(10)
	v_pk_fma_f32 v[28:29], v[28:29], v[128:129], v[92:93]
	v_pk_fma_f32 v[46:47], v[50:51], v[142:143], v[82:83]
	v_cvt_pk_bf16_f32 v48, v48, v49
	v_pk_fma_f32 v[42:43], v[42:43], v[138:139], v[86:87]
	v_cvt_pk_bf16_f32 v49, v46, v47
	v_mov_b32_e32 v240, v48
	v_mov_b32_e32 v241, v49
	v_cvt_pk_bf16_f32 v40, v40, v41
	v_cvt_pk_bf16_f32 v41, v42, v43
	v_mov_b32_e32 v242, v40
	v_mov_b32_e32 v243, v41
	v_lshl_add_u64 v[246:247], v[44:45], 0, v[244:245]
	s_nop 0
	v_permlane32_swap_b32_e32 v240, v242
	v_permlane32_swap_b32_e32 v241, v243
	s_nop 0
	v_permlane16_swap_b32_e32 v240, v242
	v_permlane16_swap_b32_e32 v241, v243
	s_nop 1
	global_store_dwordx4 v[246:247], v[240:243], off
	v_pk_fma_f32 v[38:39], v[38:39], v[134:135], v[90:91]
	v_cvt_pk_bf16_f32 v36, v36, v37
	v_pk_fma_f32 v[30:31], v[30:31], v[130:131], v[94:95]
	v_cvt_pk_bf16_f32 v37, v38, v39
	v_mov_b32_e32 v240, v36
	v_mov_b32_e32 v241, v37
	v_cvt_pk_bf16_f32 v28, v28, v29
	v_cvt_pk_bf16_f32 v29, v30, v31
	v_mov_b32_e32 v242, v28
	v_mov_b32_e32 v243, v29
	v_lshl_add_u64 v[246:247], v[44:45], 0, v[244:245]
	s_nop 0
	v_permlane32_swap_b32_e32 v240, v242
	v_permlane32_swap_b32_e32 v241, v243
	s_nop 0
	v_permlane16_swap_b32_e32 v240, v242
	v_permlane16_swap_b32_e32 v241, v243
	s_nop 1
	global_store_dwordx4 v[246:247], v[240:243], off offset:256
	v_lshlrev_b64 v[28:29], 11, v[146:147]
	v_lshl_add_u64 v[28:29], s[6:7], 0, v[28:29]
	s_waitcnt vmcnt(11)
	v_pk_fma_f32 v[32:33], v[32:33], v[140:141], v[96:97]
	v_lshl_add_u64 v[28:29], v[28:29], 0, v[160:161]
	s_waitcnt vmcnt(10)
	v_pk_fma_f32 v[24:25], v[24:25], v[136:137], v[100:101]
	s_waitcnt vmcnt(9)
	v_pk_fma_f32 v[20:21], v[20:21], v[132:133], v[104:105]
	s_waitcnt vmcnt(8)
	v_pk_fma_f32 v[12:13], v[12:13], v[128:129], v[108:109]
	v_pk_fma_f32 v[30:31], v[34:35], v[142:143], v[98:99]
	v_cvt_pk_bf16_f32 v32, v32, v33
	v_pk_fma_f32 v[26:27], v[26:27], v[138:139], v[102:103]
	v_cvt_pk_bf16_f32 v33, v30, v31
	v_mov_b32_e32 v240, v32
	v_mov_b32_e32 v241, v33
	v_cvt_pk_bf16_f32 v24, v24, v25
	v_cvt_pk_bf16_f32 v25, v26, v27
	v_mov_b32_e32 v242, v24
	v_mov_b32_e32 v243, v25
	v_lshl_add_u64 v[246:247], v[28:29], 0, v[244:245]
	s_nop 0
	v_permlane32_swap_b32_e32 v240, v242
	v_permlane32_swap_b32_e32 v241, v243
	s_nop 0
	v_permlane16_swap_b32_e32 v240, v242
	v_permlane16_swap_b32_e32 v241, v243
	s_nop 1
	global_store_dwordx4 v[246:247], v[240:243], off
	v_pk_fma_f32 v[22:23], v[22:23], v[134:135], v[106:107]
	v_cvt_pk_bf16_f32 v20, v20, v21
	v_pk_fma_f32 v[14:15], v[14:15], v[130:131], v[110:111]
	v_cvt_pk_bf16_f32 v21, v22, v23
	v_mov_b32_e32 v240, v20
	v_mov_b32_e32 v241, v21
	v_cvt_pk_bf16_f32 v12, v12, v13
	v_cvt_pk_bf16_f32 v13, v14, v15
	v_mov_b32_e32 v242, v12
	v_mov_b32_e32 v243, v13
	v_lshl_add_u64 v[246:247], v[28:29], 0, v[244:245]
	s_nop 0
	v_permlane32_swap_b32_e32 v240, v242
	v_permlane32_swap_b32_e32 v241, v243
	s_nop 0
	v_permlane16_swap_b32_e32 v240, v242
	v_permlane16_swap_b32_e32 v241, v243
	s_nop 1
	global_store_dwordx4 v[246:247], v[240:243], off offset:256
	v_lshlrev_b64 v[12:13], 11, v[164:165]
	v_lshl_add_u64 v[12:13], s[6:7], 0, v[12:13]
	s_waitcnt vmcnt(9)
	v_pk_fma_f32 v[16:17], v[16:17], v[140:141], v[112:113]
	v_lshl_add_u64 v[12:13], v[12:13], 0, v[160:161]
	s_waitcnt vmcnt(8)
	v_pk_fma_f32 v[8:9], v[8:9], v[136:137], v[116:117]
	s_waitcnt vmcnt(7)
	v_pk_fma_f32 v[4:5], v[4:5], v[132:133], v[120:121]
	s_waitcnt vmcnt(6)
	v_pk_fma_f32 v[0:1], v[0:1], v[128:129], v[124:125]
	v_pk_fma_f32 v[14:15], v[18:19], v[142:143], v[114:115]
	v_cvt_pk_bf16_f32 v16, v16, v17
	v_pk_fma_f32 v[10:11], v[10:11], v[138:139], v[118:119]
	v_cvt_pk_bf16_f32 v17, v14, v15
	v_mov_b32_e32 v240, v16
	v_mov_b32_e32 v241, v17
	v_cvt_pk_bf16_f32 v8, v8, v9
	v_cvt_pk_bf16_f32 v9, v10, v11
	v_mov_b32_e32 v242, v8
	v_mov_b32_e32 v243, v9
	v_lshl_add_u64 v[246:247], v[12:13], 0, v[244:245]
	s_nop 0
	v_permlane32_swap_b32_e32 v240, v242
	v_permlane32_swap_b32_e32 v241, v243
	s_nop 0
	v_permlane16_swap_b32_e32 v240, v242
	v_permlane16_swap_b32_e32 v241, v243
	s_nop 1
	global_store_dwordx4 v[246:247], v[240:243], off
	v_pk_fma_f32 v[6:7], v[6:7], v[134:135], v[122:123]
	v_cvt_pk_bf16_f32 v4, v4, v5
	v_pk_fma_f32 v[2:3], v[2:3], v[130:131], v[126:127]
	v_cvt_pk_bf16_f32 v5, v6, v7
	v_mov_b32_e32 v240, v4
	v_mov_b32_e32 v241, v5
	v_cvt_pk_bf16_f32 v0, v0, v1
	v_cvt_pk_bf16_f32 v1, v2, v3
	v_mov_b32_e32 v242, v0
	v_mov_b32_e32 v243, v1
	v_lshl_add_u64 v[246:247], v[12:13], 0, v[244:245]
	s_nop 0
	v_permlane32_swap_b32_e32 v240, v242
	v_permlane32_swap_b32_e32 v241, v243
	s_nop 0
	v_permlane16_swap_b32_e32 v240, v242
	v_permlane16_swap_b32_e32 v241, v243
	s_nop 1
	global_store_dwordx4 v[246:247], v[240:243], off offset:256
	s_cbranch_vccnz .LBB0_1178
	s_andn2_b64 vcc, exec, s[4:5]
	s_cbranch_vccnz .LBB0_1177
	s_barrier
	s_branch .LBB0_1177
